# gate tiles layout C: 64B per row per instr, bj halves adjacent in one 128B line
# baseline (speedup 1.0000x reference)
; __device__ __forceinline__ float bf_lo(unsigned w) { return __uint_as_float(w << 16); }
; __device__ __forceinline__ float bf_hi(unsigned w) { return __uint_as_float(w & 0xffff0000u); }
; #define EPI_LANE() int t__ = threadIdx.x; asm volatile("" : "+v"(t__)); const int wid__ = __builtin_amdgcn_readfirstlane(t__ >> 6); wr = wid__ >> 2; wc = wid__ & 3; fr = t__ & 15; fq = (t__ & 63) >> 4
;     __device__ __forceinline__ const char* gbase(int br, const Unit& u, int wid) const { return (const char*)G + ((size_t)(((br * 4 + u.pn) * 128 + u.pm) * 8 + wid)) * 16384; }
; #define RT(a, b) ((b) * __builtin_amdgcn_rcpf(a))
;     __device__ __forceinline__ void hook(f32x4 (&acc)[2][2][4][2], const Unit& u, int which, int wr, int wc, int fr, int fq) const {
;         EPI_LANE();
;         const char* gn_b = gbase(which, u, wid__); const char* gd_b = gbase(which + 1, u, wid__);
;         unsigned off0 = (unsigned)((t__ & 63) * 16); asm volatile("" : "+v"(off0));
; #pragma unroll
;         for (int ai = 0; ai < 2; ++ai) {
;                 u32x4 gnv[4][2], gdv[4][2];
; #pragma unroll
;                 for (int m = 0; m < 4; ++m)
; #pragma unroll
;                     for (int bj = 0; bj < 2; ++bj) { const unsigned off = off0 + (unsigned)(((ai * 4 + m) * 2 + bj) * 1024);
;                         gnv[m][bj] = *(const u32x4*)(gn_b + off); gdv[m][bj] = *(const u32x4*)(gd_b + off); }
; #pragma unroll
;                 for (int m = 0; m < 4; ++m)
; #pragma unroll
;                     for (int bj = 0; bj < 2; ++bj) { const u32x4 gn = gnv[m][bj], gd = gdv[m][bj];
;     ...
;                         f32x4 r0, r1;
;                         r0[0] = RT(bf_lo(gn.x), bf_lo(gd.x)); r0[1] = RT(bf_hi(gn.x), bf_hi(gd.x)); r0[2] = RT(bf_lo(gn.y), bf_lo(gd.y)); r0[3] = RT(bf_hi(gn.y), bf_hi(gd.y));
;                         r1[0] = RT(bf_lo(gn.z), bf_lo(gd.z)); r1[1] = RT(bf_hi(gn.z), bf_hi(gd.z)); r1[2] = RT(bf_lo(gn.w), bf_lo(gd.w)); r1[3] = RT(bf_hi(gn.w), bf_hi(gd.w));
;     ...
;                         acc[ai][bj][m][0] *= r0; acc[ai][bj][m][1] *= r1; }
;                 asm volatile("" : "+v"(off0) :: "memory"); }
;     }
.LBB0_52:
	s_andn2_b64 vcc, exec, s[66:67]
	s_cbranch_vccnz .LBB0_54
	v_mov_b32_e32 v96, v212
	s_nop 0
	v_readfirstlane_b32 s66, v96
	s_mov_b32 s66, 0
	s_cmp_eq_u32 s86, 4
	s_cselect_b32 s67, 0, 0x1000
	s_add_i32 s66, s66, s36
	s_add_i32 s67, s67, s31
	s_add_i32 s68, s67, s66
	s_ashr_i32 s69, s68, 31
	s_lshl_b64 s[66:67], s[68:69], 14
	s_add_u32 s66, s33, s66
	s_addc_u32 s67, s37, s67
	s_addk_i32 s68, 0x1000
	s_ashr_i32 s69, s68, 31
	v_lshlrev_b32_e32 v96, 4, v96
	s_lshl_b64 s[68:69], s[68:69], 14
	v_and_b32_e32 v96, 0x3f0, v96
	v_and_b32_e32 v98, 15, v212
	v_lshlrev_b32_e32 v98, 9, v98
	v_and_b32_e32 v99, 0x30, v212
	v_or_b32_e32 v98, v98, v99
	v_and_b32_e32 v99, 0xc0, v212
	v_lshl_or_b32 v98, v99, 1, v98
	v_and_b32_e32 v99, 0x100, v212
	v_lshl_or_b32 v96, v99, 7, v98
	s_add_u32 s68, s33, s68
	s_addc_u32 s69, s37, s69
	global_load_dwordx4 v[232:235], v96, s[66:67]
	global_load_dwordx4 v[236:239], v96, s[68:69]
	v_add_u32_e32 v98, 0x40, v96
	global_load_dwordx4 v[184:187], v98, s[66:67]
	global_load_dwordx4 v[180:183], v98, s[68:69]
	v_add_u32_e32 v98, 0x2000, v96
	global_load_dwordx4 v[176:179], v98, s[66:67]
	global_load_dwordx4 v[172:175], v98, s[68:69]
	v_add_u32_e32 v98, 0x2040, v96
	global_load_dwordx4 v[168:171], v98, s[66:67]
	global_load_dwordx4 v[164:167], v98, s[68:69]
	v_add_u32_e32 v98, 0x4000, v96
	global_load_dwordx4 v[160:163], v98, s[66:67]
	global_load_dwordx4 v[156:159], v98, s[68:69]
	v_add_u32_e32 v98, 0x4040, v96
	global_load_dwordx4 v[152:155], v98, s[66:67]
	global_load_dwordx4 v[148:151], v98, s[68:69]
	v_add_u32_e32 v98, 0x6000, v96
	global_load_dwordx4 v[136:139], v98, s[66:67]
	global_load_dwordx4 v[132:135], v98, s[68:69]
	v_add_u32_e32 v98, 0x6040, v96
	global_load_dwordx4 v[140:143], v98, s[66:67]
	global_load_dwordx4 v[144:147], v98, s[68:69]
	s_waitcnt vmcnt(0)
	v_lshlrev_b32_e32 v231, 16, v233
	v_lshlrev_b32_e32 v98, 16, v232
	v_and_b32_e32 v99, 0xffff0000, v232
	v_rcp_f32_e32 v232, v231
	v_and_b32_e32 v231, 0xffff0000, v233
	v_rcp_f32_e32 v233, v231
	v_rcp_f32_e32 v98, v98
	v_rcp_f32_e32 v99, v99
	v_lshlrev_b32_e32 v240, 16, v236
	v_and_b32_e32 v241, 0xffff0000, v236
	v_lshlrev_b32_e32 v236, 16, v237
	v_and_b32_e32 v237, 0xffff0000, v237
	v_pk_mul_f32 v[232:233], v[232:233], v[236:237]
	v_pk_mul_f32 v[98:99], v[98:99], v[240:241]
	v_pk_mul_f32 v[130:131], v[130:131], v[232:233]
	v_lshlrev_b32_e32 v232, 16, v180
	v_and_b32_e32 v233, 0xffff0000, v180
	v_lshlrev_b32_e32 v180, 16, v185
	v_pk_mul_f32 v[128:129], v[128:129], v[98:99]
	v_lshlrev_b32_e32 v98, 16, v184
	v_and_b32_e32 v99, 0xffff0000, v184
	v_rcp_f32_e32 v184, v180
	v_and_b32_e32 v180, 0xffff0000, v185
	v_rcp_f32_e32 v185, v180
	v_rcp_f32_e32 v98, v98
	v_rcp_f32_e32 v99, v99
	v_lshlrev_b32_e32 v180, 16, v181
	v_and_b32_e32 v181, 0xffff0000, v181
	v_pk_mul_f32 v[180:181], v[184:185], v[180:181]
	v_pk_mul_f32 v[98:99], v[98:99], v[232:233]
	v_pk_mul_f32 v[126:127], v[126:127], v[180:181]
	v_lshlrev_b32_e32 v180, 16, v172
	v_and_b32_e32 v181, 0xffff0000, v172
	v_lshlrev_b32_e32 v172, 16, v177
	v_pk_mul_f32 v[124:125], v[124:125], v[98:99]
	v_lshlrev_b32_e32 v98, 16, v176
	v_and_b32_e32 v99, 0xffff0000, v176
	v_rcp_f32_e32 v176, v172
	v_and_b32_e32 v172, 0xffff0000, v177
	v_rcp_f32_e32 v98, v98
	v_rcp_f32_e32 v99, v99
	v_rcp_f32_e32 v177, v172
	v_lshlrev_b32_e32 v172, 16, v173
	v_and_b32_e32 v173, 0xffff0000, v173
	v_pk_mul_f32 v[98:99], v[98:99], v[180:181]
	v_pk_mul_f32 v[172:173], v[176:177], v[172:173]
	v_pk_mul_f32 v[112:113], v[112:113], v[98:99]
	v_pk_mul_f32 v[114:115], v[114:115], v[172:173]
	v_lshlrev_b32_e32 v98, 16, v168
	v_and_b32_e32 v99, 0xffff0000, v168
	v_lshlrev_b32_e32 v172, 16, v164
	v_and_b32_e32 v173, 0xffff0000, v164
	v_lshlrev_b32_e32 v164, 16, v169
	v_rcp_f32_e32 v98, v98
	v_rcp_f32_e32 v99, v99
	v_rcp_f32_e32 v168, v164
	v_and_b32_e32 v164, 0xffff0000, v169
	v_rcp_f32_e32 v169, v164
	v_pk_mul_f32 v[98:99], v[98:99], v[172:173]
	v_lshlrev_b32_e32 v164, 16, v165
	v_and_b32_e32 v165, 0xffff0000, v165
	v_pk_mul_f32 v[164:165], v[168:169], v[164:165]
	v_pk_mul_f32 v[104:105], v[104:105], v[98:99]
	v_lshlrev_b32_e32 v98, 16, v160
	v_and_b32_e32 v99, 0xffff0000, v160
	v_pk_mul_f32 v[106:107], v[106:107], v[164:165]
	v_rcp_f32_e32 v98, v98
	v_rcp_f32_e32 v99, v99
	v_lshlrev_b32_e32 v164, 16, v156
	v_and_b32_e32 v165, 0xffff0000, v156
	v_lshlrev_b32_e32 v156, 16, v161
	v_rcp_f32_e32 v160, v156
	v_and_b32_e32 v156, 0xffff0000, v161
	v_rcp_f32_e32 v161, v156
	v_pk_mul_f32 v[98:99], v[98:99], v[164:165]
	v_lshlrev_b32_e32 v156, 16, v157
	v_and_b32_e32 v157, 0xffff0000, v157
	v_pk_mul_f32 v[92:93], v[92:93], v[98:99]
	v_lshlrev_b32_e32 v98, 16, v152
	v_and_b32_e32 v99, 0xffff0000, v152
	v_pk_mul_f32 v[156:157], v[160:161], v[156:157]
	v_rcp_f32_e32 v98, v98
	v_rcp_f32_e32 v99, v99
	v_pk_mul_f32 v[94:95], v[94:95], v[156:157]
	v_lshlrev_b32_e32 v156, 16, v148
	v_and_b32_e32 v157, 0xffff0000, v148
	v_lshlrev_b32_e32 v148, 16, v153
	v_rcp_f32_e32 v152, v148
	v_and_b32_e32 v148, 0xffff0000, v153
	v_rcp_f32_e32 v153, v148
	v_pk_mul_f32 v[98:99], v[98:99], v[156:157]
	v_lshlrev_b32_e32 v148, 16, v149
	v_pk_mul_f32 v[84:85], v[84:85], v[98:99]
	v_lshlrev_b32_e32 v98, 16, v136
	v_and_b32_e32 v99, 0xffff0000, v136
	v_and_b32_e32 v149, 0xffff0000, v149
	v_rcp_f32_e32 v98, v98
	v_rcp_f32_e32 v99, v99
	v_pk_mul_f32 v[148:149], v[152:153], v[148:149]
	v_lshlrev_b32_e32 v176, 16, v178
	v_pk_mul_f32 v[86:87], v[86:87], v[148:149]
	v_lshlrev_b32_e32 v148, 16, v132
	v_and_b32_e32 v149, 0xffff0000, v132
	v_lshlrev_b32_e32 v132, 16, v137
	v_rcp_f32_e32 v136, v132
	v_and_b32_e32 v132, 0xffff0000, v137
	v_pk_mul_f32 v[98:99], v[98:99], v[148:149]
; __device__ __forceinline__ float bf_lo(unsigned w) { return __uint_as_float(w << 16); }
; __device__ __forceinline__ float bf_hi(unsigned w) { return __uint_as_float(w & 0xffff0000u); }
; #define EPI_LANE() int t__ = threadIdx.x; asm volatile("" : "+v"(t__)); const int wid__ = __builtin_amdgcn_readfirstlane(t__ >> 6); wr = wid__ >> 2; wc = wid__ & 3; fr = t__ & 15; fq = (t__ & 63) >> 4
;     __device__ __forceinline__ const char* gbase(int br, const Unit& u, int wid) const { return (const char*)G + ((size_t)(((br * 4 + u.pn) * 128 + u.pm) * 8 + wid)) * 16384; }
; #define RT(a, b) ((b) * __builtin_amdgcn_rcpf(a))
;     __device__ __forceinline__ void hook(f32x4 (&acc)[2][2][4][2], const Unit& u, int which, int wr, int wc, int fr, int fq) const {
;         EPI_LANE();
;         const char* gn_b = gbase(which, u, wid__); const char* gd_b = gbase(which + 1, u, wid__);
;         unsigned off0 = (unsigned)((t__ & 63) * 16); asm volatile("" : "+v"(off0));
; #pragma unroll
;         for (int ai = 0; ai < 2; ++ai) {
;                 u32x4 gnv[4][2], gdv[4][2];
; #pragma unroll
;                 for (int m = 0; m < 4; ++m)
; #pragma unroll
;                     for (int bj = 0; bj < 2; ++bj) { const unsigned off = off0 + (unsigned)(((ai * 4 + m) * 2 + bj) * 1024);
;                         gnv[m][bj] = *(const u32x4*)(gn_b + off); gdv[m][bj] = *(const u32x4*)(gd_b + off); }
; #pragma unroll
;                 for (int m = 0; m < 4; ++m)
; #pragma unroll
;                     for (int bj = 0; bj < 2; ++bj) { const u32x4 gn = gnv[m][bj], gd = gdv[m][bj];
;     ...
;                         f32x4 r0, r1;
;                         r0[0] = RT(bf_lo(gn.x), bf_lo(gd.x)); r0[1] = RT(bf_hi(gn.x), bf_hi(gd.x)); r0[2] = RT(bf_lo(gn.y), bf_lo(gd.y)); r0[3] = RT(bf_hi(gn.y), bf_hi(gd.y));
;                         r1[0] = RT(bf_lo(gn.z), bf_lo(gd.z)); r1[1] = RT(bf_hi(gn.z), bf_hi(gd.z)); r1[2] = RT(bf_lo(gn.w), bf_lo(gd.w)); r1[3] = RT(bf_hi(gn.w), bf_hi(gd.w));
;     ...
;                         acc[ai][bj][m][0] *= r0; acc[ai][bj][m][1] *= r1; }
;                 asm volatile("" : "+v"(off0) :: "memory"); }
;     }
	v_rcp_f32_e32 v137, v132
	v_pk_mul_f32 v[76:77], v[76:77], v[98:99]
	v_lshlrev_b32_e32 v98, 16, v140
	v_and_b32_e32 v99, 0xffff0000, v140
	v_and_b32_e32 v177, 0xffff0000, v178
	v_lshlrev_b32_e32 v180, 16, v174
	v_and_b32_e32 v181, 0xffff0000, v174
	v_lshlrev_b32_e32 v174, 16, v179
	v_lshlrev_b32_e32 v168, 16, v170
	v_and_b32_e32 v169, 0xffff0000, v170
	v_lshlrev_b32_e32 v172, 16, v166
	v_and_b32_e32 v173, 0xffff0000, v166
	v_lshlrev_b32_e32 v166, 16, v171
	v_rcp_f32_e32 v98, v98
	v_rcp_f32_e32 v99, v99
	v_rcp_f32_e32 v176, v176
	v_rcp_f32_e32 v177, v177
	v_rcp_f32_e32 v178, v174
	v_and_b32_e32 v174, 0xffff0000, v179
	v_rcp_f32_e32 v168, v168
	v_rcp_f32_e32 v169, v169
	v_rcp_f32_e32 v170, v166
	v_and_b32_e32 v166, 0xffff0000, v171
	v_lshlrev_b32_e32 v132, 16, v133
	v_and_b32_e32 v133, 0xffff0000, v133
	v_rcp_f32_e32 v179, v174
	v_rcp_f32_e32 v171, v166
	v_pk_mul_f32 v[132:133], v[136:137], v[132:133]
	v_lshlrev_b32_e32 v232, 16, v182
	v_pk_mul_f32 v[78:79], v[78:79], v[132:133]
	v_lshlrev_b32_e32 v132, 16, v144
	v_and_b32_e32 v133, 0xffff0000, v144
	v_pk_mul_f32 v[98:99], v[98:99], v[132:133]
	v_and_b32_e32 v233, 0xffff0000, v182
	v_lshlrev_b32_e32 v182, 16, v187
	v_pk_mul_f32 v[176:177], v[176:177], v[180:181]
	v_lshlrev_b32_e32 v174, 16, v175
	v_and_b32_e32 v175, 0xffff0000, v175
	v_pk_mul_f32 v[168:169], v[168:169], v[172:173]
	v_lshlrev_b32_e32 v166, 16, v167
	v_and_b32_e32 v167, 0xffff0000, v167
	v_pk_mul_f32 v[68:69], v[68:69], v[98:99]
	v_add_u32_e32 v98, 0x10000, v96
	v_lshlrev_b32_e32 v184, 16, v186
	v_and_b32_e32 v185, 0xffff0000, v186
	v_rcp_f32_e32 v186, v182
	v_and_b32_e32 v182, 0xffff0000, v187
	v_pk_mul_f32 v[174:175], v[178:179], v[174:175]
	v_pk_mul_f32 v[108:109], v[108:109], v[176:177]
	v_pk_mul_f32 v[166:167], v[170:171], v[166:167]
	v_pk_mul_f32 v[100:101], v[100:101], v[168:169]
	global_load_dwordx4 v[168:171], v98, s[66:67]
	global_load_dwordx4 v[176:179], v98, s[68:69]
	v_rcp_f32_e32 v184, v184
	v_rcp_f32_e32 v185, v185
	v_rcp_f32_e32 v187, v182
	v_lshlrev_b32_e32 v231, 16, v234
	v_lshlrev_b32_e32 v182, 16, v183
	v_and_b32_e32 v183, 0xffff0000, v183
	v_rcp_f32_e32 v236, v231
	v_and_b32_e32 v231, 0xffff0000, v234
	v_pk_mul_f32 v[184:185], v[184:185], v[232:233]
	v_pk_mul_f32 v[182:183], v[186:187], v[182:183]
	v_add_u32_e32 v98, 0x10040, v96
	v_rcp_f32_e32 v237, v231
	v_lshlrev_b32_e32 v231, 16, v235
	v_pk_mul_f32 v[118:119], v[118:119], v[182:183]
	v_pk_mul_f32 v[116:117], v[116:117], v[184:185]
	global_load_dwordx4 v[180:183], v98, s[66:67]
	global_load_dwordx4 v[184:187], v98, s[68:69]
	v_rcp_f32_e32 v234, v231
	v_and_b32_e32 v231, 0xffff0000, v235
	v_rcp_f32_e32 v235, v231
	v_lshlrev_b32_e32 v240, 16, v238
	v_and_b32_e32 v241, 0xffff0000, v238
	v_lshlrev_b32_e32 v238, 16, v239
	v_and_b32_e32 v239, 0xffff0000, v239
	v_pk_mul_f32 v[236:237], v[236:237], v[240:241]
	v_pk_mul_f32 v[234:235], v[234:235], v[238:239]
	v_add_u32_e32 v98, 0x12000, v96
	v_pk_mul_f32 v[122:123], v[122:123], v[234:235]
	v_pk_mul_f32 v[120:121], v[120:121], v[236:237]
	global_load_dwordx4 v[232:235], v98, s[66:67]
	global_load_dwordx4 v[236:239], v98, s[68:69]
	v_lshlrev_b32_e32 v160, 16, v162
	v_and_b32_e32 v161, 0xffff0000, v162
	v_rcp_f32_e32 v160, v160
	v_rcp_f32_e32 v161, v161
	v_lshlrev_b32_e32 v164, 16, v158
	v_and_b32_e32 v165, 0xffff0000, v158
	v_add_u32_e32 v98, 0x12040, v96
	v_pk_mul_f32 v[110:111], v[110:111], v[174:175]
	v_pk_mul_f32 v[102:103], v[102:103], v[166:167]
	v_pk_mul_f32 v[160:161], v[160:161], v[164:165]
	global_load_dwordx4 v[172:175], v98, s[66:67]
	global_load_dwordx4 v[164:167], v98, s[68:69]
	v_lshlrev_b32_e32 v158, 16, v163
	v_rcp_f32_e32 v162, v158
	v_and_b32_e32 v158, 0xffff0000, v163
	v_rcp_f32_e32 v163, v158
	v_lshlrev_b32_e32 v152, 16, v154
	v_and_b32_e32 v153, 0xffff0000, v154
	v_rcp_f32_e32 v152, v152
	v_rcp_f32_e32 v153, v153
	v_lshlrev_b32_e32 v158, 16, v159
	v_and_b32_e32 v159, 0xffff0000, v159
	v_pk_mul_f32 v[158:159], v[162:163], v[158:159]
	v_lshlrev_b32_e32 v156, 16, v150
	v_and_b32_e32 v157, 0xffff0000, v150
	v_add_u32_e32 v98, 0x14000, v96
	v_pk_mul_f32 v[90:91], v[90:91], v[158:159]
	v_pk_mul_f32 v[88:89], v[88:89], v[160:161]
	v_pk_mul_f32 v[152:153], v[152:153], v[156:157]
	v_lshlrev_b32_e32 v150, 16, v155
	global_load_dwordx4 v[160:163], v98, s[66:67]
	global_load_dwordx4 v[156:159], v98, s[68:69]
	v_rcp_f32_e32 v154, v150
	v_and_b32_e32 v150, 0xffff0000, v155
	v_lshlrev_b32_e32 v148, 16, v134
	v_and_b32_e32 v149, 0xffff0000, v134
	v_lshlrev_b32_e32 v134, 16, v139
	v_rcp_f32_e32 v155, v150
	v_lshlrev_b32_e32 v136, 16, v138
	v_and_b32_e32 v137, 0xffff0000, v138
	v_rcp_f32_e32 v138, v134
	v_and_b32_e32 v134, 0xffff0000, v139
	v_rcp_f32_e32 v136, v136
	v_rcp_f32_e32 v137, v137
	v_rcp_f32_e32 v139, v134
	v_lshlrev_b32_e32 v132, 16, v141
	v_and_b32_e32 v133, 0xffff0000, v141
	v_lshlrev_b32_e32 v150, 16, v151
	v_and_b32_e32 v151, 0xffff0000, v151
	v_rcp_f32_e32 v132, v132
	v_rcp_f32_e32 v133, v133
	v_pk_mul_f32 v[150:151], v[154:155], v[150:151]
	v_lshlrev_b32_e32 v134, 16, v135
	v_and_b32_e32 v135, 0xffff0000, v135
	v_add_u32_e32 v98, 0x14040, v96
	v_pk_mul_f32 v[82:83], v[82:83], v[150:151]
	v_pk_mul_f32 v[80:81], v[80:81], v[152:153]
	v_pk_mul_f32 v[136:137], v[136:137], v[148:149]
	v_pk_mul_f32 v[134:135], v[138:139], v[134:135]
	global_load_dwordx4 v[152:155], v98, s[66:67]
	global_load_dwordx4 v[148:151], v98, s[68:69]
	v_pk_mul_f32 v[74:75], v[74:75], v[134:135]
	v_lshlrev_b32_e32 v134, 16, v145
	v_and_b32_e32 v135, 0xffff0000, v145
	v_pk_mul_f32 v[132:133], v[132:133], v[134:135]
	v_lshlrev_b32_e32 v134, 16, v142
	v_and_b32_e32 v135, 0xffff0000, v142
	v_rcp_f32_e32 v134, v134
	v_rcp_f32_e32 v135, v135
	v_pk_mul_f32 v[72:73], v[72:73], v[136:137]
	v_lshlrev_b32_e32 v136, 16, v146
	v_and_b32_e32 v137, 0xffff0000, v146
	v_add_u32_e32 v98, 0x16000, v96
	v_pk_mul_f32 v[134:135], v[134:135], v[136:137]
	v_lshlrev_b32_e32 v136, 16, v143
	v_and_b32_e32 v137, 0xffff0000, v143
	v_lshlrev_b32_e32 v138, 16, v147
	v_and_b32_e32 v139, 0xffff0000, v147
	global_load_dwordx4 v[144:147], v98, s[66:67]
	global_load_dwordx4 v[140:143], v98, s[68:69]
	v_rcp_f32_e32 v136, v136
	v_rcp_f32_e32 v137, v137
	v_add_u32_e32 v98, 0x16040, v96
	v_pk_mul_f32 v[70:71], v[70:71], v[132:133]
	v_pk_mul_f32 v[64:65], v[64:65], v[134:135]
	v_pk_mul_f32 v[136:137], v[136:137], v[138:139]
	s_waitcnt vmcnt(0)
; __device__ __forceinline__ float bf_lo(unsigned w) { return __uint_as_float(w << 16); }
; __device__ __forceinline__ float bf_hi(unsigned w) { return __uint_as_float(w & 0xffff0000u); }
; #define EPI_LANE() int t__ = threadIdx.x; asm volatile("" : "+v"(t__)); const int wid__ = __builtin_amdgcn_readfirstlane(t__ >> 6); wr = wid__ >> 2; wc = wid__ & 3; fr = t__ & 15; fq = (t__ & 63) >> 4
;     __device__ __forceinline__ const char* gbase(int br, const Unit& u, int wid) const { return (const char*)G + ((size_t)(((br * 4 + u.pn) * 128 + u.pm) * 8 + wid)) * 16384; }
; #define RT(a, b) ((b) * __builtin_amdgcn_rcpf(a))
;     __device__ __forceinline__ void hook(f32x4 (&acc)[2][2][4][2], const Unit& u, int which, int wr, int wc, int fr, int fq) const {
;         EPI_LANE();
;         const char* gn_b = gbase(which, u, wid__); const char* gd_b = gbase(which + 1, u, wid__);
;         unsigned off0 = (unsigned)((t__ & 63) * 16); asm volatile("" : "+v"(off0));
; #pragma unroll
;         for (int ai = 0; ai < 2; ++ai) {
;                 u32x4 gnv[4][2], gdv[4][2];
; #pragma unroll
;                 for (int m = 0; m < 4; ++m)
; #pragma unroll
;                     for (int bj = 0; bj < 2; ++bj) { const unsigned off = off0 + (unsigned)(((ai * 4 + m) * 2 + bj) * 1024);
;                         gnv[m][bj] = *(const u32x4*)(gn_b + off); gdv[m][bj] = *(const u32x4*)(gd_b + off); }
; #pragma unroll
;                 for (int m = 0; m < 4; ++m)
; #pragma unroll
;                     for (int bj = 0; bj < 2; ++bj) { const u32x4 gn = gnv[m][bj], gd = gdv[m][bj];
;     ...
;                         f32x4 r0, r1;
;                         r0[0] = RT(bf_lo(gn.x), bf_lo(gd.x)); r0[1] = RT(bf_hi(gn.x), bf_hi(gd.x)); r0[2] = RT(bf_lo(gn.y), bf_lo(gd.y)); r0[3] = RT(bf_hi(gn.y), bf_hi(gd.y));
;                         r1[0] = RT(bf_lo(gn.z), bf_lo(gd.z)); r1[1] = RT(bf_hi(gn.z), bf_hi(gd.z)); r1[2] = RT(bf_lo(gn.w), bf_lo(gd.w)); r1[3] = RT(bf_hi(gn.w), bf_hi(gd.w));
;     ...
;                         acc[ai][bj][m][0] *= r0; acc[ai][bj][m][1] *= r1; }
;                 asm volatile("" : "+v"(off0) :: "memory"); }
;     }
	v_and_b32_e32 v99, 0xffff0000, v168
	v_pk_mul_f32 v[66:67], v[66:67], v[136:137]
	global_load_dwordx4 v[136:139], v98, s[66:67]
	global_load_dwordx4 v[132:135], v98, s[68:69]
	v_lshlrev_b32_e32 v98, 16, v168
	v_rcp_f32_e32 v98, v98
	v_rcp_f32_e32 v99, v99
	v_lshlrev_b32_e32 v168, 16, v169
	v_and_b32_e32 v169, 0xffff0000, v169
	v_lshlrev_b32_e32 v240, 16, v176
	v_and_b32_e32 v241, 0xffff0000, v176
	v_rcp_f32_e32 v168, v168
	v_rcp_f32_e32 v169, v169
	v_pk_mul_f32 v[98:99], v[98:99], v[240:241]
	v_lshlrev_b32_e32 v176, 16, v177
	v_pk_mul_f32 v[60:61], v[60:61], v[98:99]
	v_lshlrev_b32_e32 v98, 16, v180
	v_and_b32_e32 v99, 0xffff0000, v180
	v_and_b32_e32 v177, 0xffff0000, v177
	v_rcp_f32_e32 v98, v98
	v_rcp_f32_e32 v99, v99
	v_pk_mul_f32 v[168:169], v[168:169], v[176:177]
	v_lshlrev_b32_e32 v176, 16, v170
	v_and_b32_e32 v170, 0xffff0000, v170
	v_rcp_f32_e32 v177, v170
	v_lshlrev_b32_e32 v170, 16, v171
	v_and_b32_e32 v171, 0xffff0000, v171
	v_rcp_f32_e32 v170, v170
	v_rcp_f32_e32 v171, v171
	v_pk_mul_f32 v[62:63], v[62:63], v[168:169]
	v_lshlrev_b32_e32 v168, 16, v184
	v_and_b32_e32 v169, 0xffff0000, v184
	v_pk_mul_f32 v[98:99], v[98:99], v[168:169]
	v_lshlrev_b32_e32 v168, 16, v181
	v_and_b32_e32 v169, 0xffff0000, v181
	v_rcp_f32_e32 v168, v168
	v_rcp_f32_e32 v169, v169
	v_lshlrev_b32_e32 v240, 16, v178
	v_and_b32_e32 v241, 0xffff0000, v178
	v_lshlrev_b32_e32 v178, 16, v179
	v_and_b32_e32 v179, 0xffff0000, v179
	v_pk_mul_f32 v[52:53], v[52:53], v[98:99]
	v_lshlrev_b32_e32 v98, 16, v232
	v_and_b32_e32 v99, 0xffff0000, v232
	v_pk_mul_f32 v[170:171], v[170:171], v[178:179]
	v_rcp_f32_e32 v98, v98
	v_rcp_f32_e32 v99, v99
	v_rcp_f32_e32 v176, v176
	v_pk_mul_f32 v[58:59], v[58:59], v[170:171]
	v_lshlrev_b32_e32 v170, 16, v185
	v_and_b32_e32 v171, 0xffff0000, v185
	v_pk_mul_f32 v[168:169], v[168:169], v[170:171]
	v_lshlrev_b32_e32 v170, 16, v182
	v_and_b32_e32 v171, 0xffff0000, v182
	v_rcp_f32_e32 v170, v170
	v_rcp_f32_e32 v171, v171
	v_pk_mul_f32 v[54:55], v[54:55], v[168:169]
	v_lshlrev_b32_e32 v168, 16, v236
	v_and_b32_e32 v169, 0xffff0000, v236
	v_pk_mul_f32 v[98:99], v[98:99], v[168:169]
	v_lshlrev_b32_e32 v168, 16, v233
	v_and_b32_e32 v169, 0xffff0000, v233
	v_pk_mul_f32 v[176:177], v[176:177], v[240:241]
	v_rcp_f32_e32 v168, v168
	v_rcp_f32_e32 v169, v169
	v_pk_mul_f32 v[56:57], v[56:57], v[176:177]
	v_lshlrev_b32_e32 v176, 16, v186
	v_and_b32_e32 v177, 0xffff0000, v186
	v_pk_mul_f32 v[44:45], v[44:45], v[98:99]
	v_lshlrev_b32_e32 v98, 16, v172
	v_and_b32_e32 v99, 0xffff0000, v172
	v_pk_mul_f32 v[170:171], v[170:171], v[176:177]
	v_rcp_f32_e32 v98, v98
	v_rcp_f32_e32 v99, v99
	v_pk_mul_f32 v[48:49], v[48:49], v[170:171]
	v_lshlrev_b32_e32 v170, 16, v237
	v_and_b32_e32 v171, 0xffff0000, v237
	v_pk_mul_f32 v[168:169], v[168:169], v[170:171]
	v_lshlrev_b32_e32 v176, 16, v183
	v_pk_mul_f32 v[46:47], v[46:47], v[168:169]
	v_lshlrev_b32_e32 v168, 16, v164
	v_and_b32_e32 v169, 0xffff0000, v164
	v_lshlrev_b32_e32 v164, 16, v173
	v_pk_mul_f32 v[98:99], v[98:99], v[168:169]
	v_rcp_f32_e32 v168, v164
	v_and_b32_e32 v164, 0xffff0000, v173
	v_rcp_f32_e32 v169, v164
	v_lshlrev_b32_e32 v164, 16, v165
	v_and_b32_e32 v165, 0xffff0000, v165
	v_pk_mul_f32 v[36:37], v[36:37], v[98:99]
	v_pk_mul_f32 v[164:165], v[168:169], v[164:165]
	v_lshlrev_b32_e32 v98, 16, v160
	v_pk_mul_f32 v[38:39], v[38:39], v[164:165]
	v_lshlrev_b32_e32 v164, 16, v156
	v_and_b32_e32 v165, 0xffff0000, v156
	v_lshlrev_b32_e32 v156, 16, v161
	v_and_b32_e32 v99, 0xffff0000, v160
	v_rcp_f32_e32 v160, v156
	v_and_b32_e32 v156, 0xffff0000, v161
	v_rcp_f32_e32 v161, v156
	v_rcp_f32_e32 v98, v98
	v_rcp_f32_e32 v99, v99
	v_lshlrev_b32_e32 v156, 16, v157
	v_and_b32_e32 v157, 0xffff0000, v157
	v_pk_mul_f32 v[156:157], v[160:161], v[156:157]
	v_pk_mul_f32 v[98:99], v[98:99], v[164:165]
	v_pk_mul_f32 v[30:31], v[30:31], v[156:157]
	v_lshlrev_b32_e32 v156, 16, v148
	v_and_b32_e32 v157, 0xffff0000, v148
	v_lshlrev_b32_e32 v148, 16, v153
	v_pk_mul_f32 v[28:29], v[28:29], v[98:99]
	v_lshlrev_b32_e32 v98, 16, v152
	v_and_b32_e32 v99, 0xffff0000, v152
	v_rcp_f32_e32 v152, v148
	v_and_b32_e32 v148, 0xffff0000, v153
	v_rcp_f32_e32 v153, v148
	v_rcp_f32_e32 v98, v98
	v_rcp_f32_e32 v99, v99
	v_lshlrev_b32_e32 v148, 16, v149
	v_and_b32_e32 v149, 0xffff0000, v149
	v_pk_mul_f32 v[148:149], v[152:153], v[148:149]
	v_pk_mul_f32 v[98:99], v[98:99], v[156:157]
	v_pk_mul_f32 v[22:23], v[22:23], v[148:149]
	v_lshlrev_b32_e32 v148, 16, v140
	v_and_b32_e32 v149, 0xffff0000, v140
	v_lshlrev_b32_e32 v140, 16, v145
	v_pk_mul_f32 v[20:21], v[20:21], v[98:99]
	v_lshlrev_b32_e32 v98, 16, v144
	v_and_b32_e32 v99, 0xffff0000, v144
	v_rcp_f32_e32 v144, v140
	v_and_b32_e32 v140, 0xffff0000, v145
	v_rcp_f32_e32 v98, v98
	v_rcp_f32_e32 v99, v99
	v_rcp_f32_e32 v145, v140
	v_and_b32_e32 v177, 0xffff0000, v183
	v_rcp_f32_e32 v176, v176
	v_rcp_f32_e32 v177, v177
	v_lshlrev_b32_e32 v140, 16, v141
	v_and_b32_e32 v141, 0xffff0000, v141
	v_lshlrev_b32_e32 v170, 16, v234
	v_and_b32_e32 v171, 0xffff0000, v234
	v_pk_mul_f32 v[98:99], v[98:99], v[148:149]
	v_pk_mul_f32 v[140:141], v[144:145], v[140:141]
	v_rcp_f32_e32 v170, v170
	v_rcp_f32_e32 v171, v171
	v_pk_mul_f32 v[18:19], v[18:19], v[140:141]
	v_pk_mul_f32 v[16:17], v[16:17], v[98:99]
	s_waitcnt vmcnt(0)
; __device__ __forceinline__ float bf_lo(unsigned w) { return __uint_as_float(w << 16); }
; __device__ __forceinline__ float bf_hi(unsigned w) { return __uint_as_float(w & 0xffff0000u); }
; #define EPI_LANE() int t__ = threadIdx.x; asm volatile("" : "+v"(t__)); const int wid__ = __builtin_amdgcn_readfirstlane(t__ >> 6); wr = wid__ >> 2; wc = wid__ & 3; fr = t__ & 15; fq = (t__ & 63) >> 4
;     __device__ __forceinline__ const char* gbase(int br, const Unit& u, int wid) const { return (const char*)G + ((size_t)(((br * 4 + u.pn) * 128 + u.pm) * 8 + wid)) * 16384; }
; #define RT(a, b) ((b) * __builtin_amdgcn_rcpf(a))
;     __device__ __forceinline__ void hook(f32x4 (&acc)[2][2][4][2], const Unit& u, int which, int wr, int wc, int fr, int fq) const {
;         EPI_LANE();
;         const char* gn_b = gbase(which, u, wid__); const char* gd_b = gbase(which + 1, u, wid__);
;         unsigned off0 = (unsigned)((t__ & 63) * 16); asm volatile("" : "+v"(off0));
; #pragma unroll
;         for (int ai = 0; ai < 2; ++ai) {
;                 u32x4 gnv[4][2], gdv[4][2];
; #pragma unroll
;                 for (int m = 0; m < 4; ++m)
; #pragma unroll
;                     for (int bj = 0; bj < 2; ++bj) { const unsigned off = off0 + (unsigned)(((ai * 4 + m) * 2 + bj) * 1024);
;                         gnv[m][bj] = *(const u32x4*)(gn_b + off); gdv[m][bj] = *(const u32x4*)(gd_b + off); }
; #pragma unroll
;                 for (int m = 0; m < 4; ++m)
; #pragma unroll
;                     for (int bj = 0; bj < 2; ++bj) { const u32x4 gn = gnv[m][bj], gd = gdv[m][bj];
;     ...
;                         f32x4 r0, r1;
;                         r0[0] = RT(bf_lo(gn.x), bf_lo(gd.x)); r0[1] = RT(bf_hi(gn.x), bf_hi(gd.x)); r0[2] = RT(bf_lo(gn.y), bf_lo(gd.y)); r0[3] = RT(bf_hi(gn.y), bf_hi(gd.y));
;                         r1[0] = RT(bf_lo(gn.z), bf_lo(gd.z)); r1[1] = RT(bf_hi(gn.z), bf_hi(gd.z)); r1[2] = RT(bf_lo(gn.w), bf_lo(gd.w)); r1[3] = RT(bf_hi(gn.w), bf_hi(gd.w));
;     ...
;                         acc[ai][bj][m][0] *= r0; acc[ai][bj][m][1] *= r1; }
;                 asm volatile("" : "+v"(off0) :: "memory"); }
;     }
	v_lshlrev_b32_e32 v98, 16, v136
	v_and_b32_e32 v99, 0xffff0000, v136
	v_lshlrev_b32_e32 v140, 16, v132
	v_and_b32_e32 v141, 0xffff0000, v132
	v_lshlrev_b32_e32 v132, 16, v137
	v_lshlrev_b32_e32 v178, 16, v187
	v_and_b32_e32 v179, 0xffff0000, v187
	v_lshlrev_b32_e32 v168, 16, v174
	v_and_b32_e32 v169, 0xffff0000, v174
	v_rcp_f32_e32 v98, v98
	v_rcp_f32_e32 v99, v99
	v_rcp_f32_e32 v136, v132
	v_and_b32_e32 v132, 0xffff0000, v137
	v_pk_mul_f32 v[176:177], v[176:177], v[178:179]
	v_rcp_f32_e32 v168, v168
	v_rcp_f32_e32 v169, v169
	v_rcp_f32_e32 v137, v132
	v_pk_mul_f32 v[50:51], v[50:51], v[176:177]
	v_lshlrev_b32_e32 v176, 16, v238
	v_and_b32_e32 v177, 0xffff0000, v238
	v_pk_mul_f32 v[170:171], v[170:171], v[176:177]
	v_lshlrev_b32_e32 v164, 16, v158
	v_pk_mul_f32 v[40:41], v[40:41], v[170:171]
	v_lshlrev_b32_e32 v170, 16, v166
	v_and_b32_e32 v171, 0xffff0000, v166
	v_lshlrev_b32_e32 v166, 16, v175
	v_and_b32_e32 v165, 0xffff0000, v158
	v_lshlrev_b32_e32 v158, 16, v163
	v_lshlrev_b32_e32 v156, 16, v150
	v_and_b32_e32 v157, 0xffff0000, v150
	v_lshlrev_b32_e32 v150, 16, v155
	v_lshlrev_b32_e32 v148, 16, v142
	v_and_b32_e32 v149, 0xffff0000, v142
	v_lshlrev_b32_e32 v142, 16, v147
	v_pk_mul_f32 v[98:99], v[98:99], v[140:141]
	v_lshlrev_b32_e32 v132, 16, v133
	v_and_b32_e32 v133, 0xffff0000, v133
	v_lshlrev_b32_e32 v140, 16, v134
	v_and_b32_e32 v141, 0xffff0000, v134
	v_lshlrev_b32_e32 v134, 16, v139
	v_lshlrev_b32_e32 v176, 16, v235
	v_and_b32_e32 v177, 0xffff0000, v235
	v_pk_mul_f32 v[168:169], v[168:169], v[170:171]
	v_rcp_f32_e32 v170, v166
	v_and_b32_e32 v166, 0xffff0000, v175
	v_lshlrev_b32_e32 v160, 16, v162
	v_and_b32_e32 v161, 0xffff0000, v162
	v_rcp_f32_e32 v162, v158
	v_and_b32_e32 v158, 0xffff0000, v163
	v_lshlrev_b32_e32 v152, 16, v154
	v_and_b32_e32 v153, 0xffff0000, v154
	v_rcp_f32_e32 v154, v150
	v_and_b32_e32 v150, 0xffff0000, v155
	v_lshlrev_b32_e32 v144, 16, v146
	v_and_b32_e32 v145, 0xffff0000, v146
	v_rcp_f32_e32 v146, v142
	v_and_b32_e32 v142, 0xffff0000, v147
	v_pk_mul_f32 v[132:133], v[136:137], v[132:133]
	v_lshlrev_b32_e32 v136, 16, v138
	v_and_b32_e32 v137, 0xffff0000, v138
	v_rcp_f32_e32 v138, v134
	v_and_b32_e32 v134, 0xffff0000, v139
	v_rcp_f32_e32 v176, v176
	v_rcp_f32_e32 v177, v177
	v_rcp_f32_e32 v171, v166
	v_rcp_f32_e32 v160, v160
	v_rcp_f32_e32 v161, v161
	v_rcp_f32_e32 v163, v158
	v_rcp_f32_e32 v152, v152
	v_rcp_f32_e32 v153, v153
	v_rcp_f32_e32 v155, v150
	v_rcp_f32_e32 v144, v144
	v_rcp_f32_e32 v145, v145
	v_rcp_f32_e32 v147, v142
	v_rcp_f32_e32 v136, v136
	v_rcp_f32_e32 v137, v137
	v_rcp_f32_e32 v139, v134
	v_lshlrev_b32_e32 v178, 16, v239
	v_and_b32_e32 v179, 0xffff0000, v239
	v_lshlrev_b32_e32 v166, 16, v167
	v_and_b32_e32 v167, 0xffff0000, v167
	v_lshlrev_b32_e32 v158, 16, v159
	v_and_b32_e32 v159, 0xffff0000, v159
	v_lshlrev_b32_e32 v150, 16, v151
	v_and_b32_e32 v151, 0xffff0000, v151
	v_lshlrev_b32_e32 v142, 16, v143
	v_and_b32_e32 v143, 0xffff0000, v143
	v_lshlrev_b32_e32 v134, 16, v135
	v_and_b32_e32 v135, 0xffff0000, v135
	v_pk_mul_f32 v[176:177], v[176:177], v[178:179]
	v_pk_mul_f32 v[166:167], v[170:171], v[166:167]
	v_pk_mul_f32 v[160:161], v[160:161], v[164:165]
	v_pk_mul_f32 v[158:159], v[162:163], v[158:159]
	v_pk_mul_f32 v[152:153], v[152:153], v[156:157]
	v_pk_mul_f32 v[150:151], v[154:155], v[150:151]
	v_pk_mul_f32 v[144:145], v[144:145], v[148:149]
	v_pk_mul_f32 v[142:143], v[146:147], v[142:143]
	v_pk_mul_f32 v[136:137], v[136:137], v[140:141]
	v_pk_mul_f32 v[134:135], v[138:139], v[134:135]
	v_pk_mul_f32 v[42:43], v[42:43], v[176:177]
	v_pk_mul_f32 v[34:35], v[34:35], v[166:167]
	v_pk_mul_f32 v[32:33], v[32:33], v[168:169]
	v_pk_mul_f32 v[26:27], v[26:27], v[158:159]
	v_pk_mul_f32 v[24:25], v[24:25], v[160:161]
	v_pk_mul_f32 v[14:15], v[14:15], v[150:151]
	v_pk_mul_f32 v[12:13], v[12:13], v[152:153]
	v_pk_mul_f32 v[10:11], v[10:11], v[142:143]
	v_pk_mul_f32 v[8:9], v[8:9], v[144:145]
	v_pk_mul_f32 v[6:7], v[6:7], v[132:133]
	v_pk_mul_f32 v[4:5], v[4:5], v[98:99]
	v_pk_mul_f32 v[2:3], v[2:3], v[134:135]
	v_pk_mul_f32 v[0:1], v[0:1], v[136:137]

; __device__ __forceinline__ float bf_lo(unsigned w) { return __uint_as_float(w << 16); }
; __device__ __forceinline__ float bf_hi(unsigned w) { return __uint_as_float(w & 0xffff0000u); }
; __device__ __forceinline__ unsigned cvt_pk_bf16(float lo, float hi) { f32x2_t v = {lo, hi}; bf16x2_t b = __builtin_convertvector(v, bf16x2_t); return __builtin_bit_cast(unsigned, b); }
; #define EPI_LANE() int t__ = threadIdx.x; asm volatile("" : "+v"(t__)); const int wid__ = __builtin_amdgcn_readfirstlane(t__ >> 6); wr = wid__ >> 2; wc = wid__ & 3; fr = t__ & 15; fq = (t__ & 63) >> 4
;     __device__ __forceinline__ void operator()(const f32x4 (&acc)[2][2][4][2], const Unit& u, int wr, int wc, int fr, int fq) const {
;         EPI_LANE();
;         const char* g_b = gbase(2, u, wid__) + (t__ & 63) * 16; char* mb = (char*)(Mg + (size_t)u.pm * BM * 1024 + u.pn * BM);
;         unsigned rl0 = (unsigned)(wr * 64 + fr), cl0 = (unsigned)(wc * 32 + 8 * fq); asm volatile("" : "+v"(rl0), "+v"(cl0));
; #pragma unroll
;         for (int ai = 0; ai < 2; ++ai) {
;             u32x4 gv[4][2];
; #pragma unroll
;             for (int m = 0; m < 4; ++m)
; #pragma unroll
;                 for (int bj = 0; bj < 2; ++bj) gv[m][bj] = *(const u32x4*)(g_b + ((ai * 4 + m) * 2 + bj) * 1024);
; #pragma unroll
;             for (int m = 0; m < 4; ++m) { const unsigned rl = rl0 + (unsigned)(ai * HALF + m * 16);
; #pragma unroll
;                 for (int bj = 0; bj < 2; ++bj) { const unsigned cl = cl0 + (unsigned)(bj * HALF);
;                     const u32x4 g = gv[m][bj];
;                     const f32x4 v0 = acc[ai][bj][m][0], v1 = acc[ai][bj][m][1];
;                     u32x4 w;
;                     w.x = cvt_pk_bf16(v0[0] * __builtin_amdgcn_rcpf(bf_lo(g.x)), v0[1] * __builtin_amdgcn_rcpf(bf_hi(g.x)));
;                     w.y = cvt_pk_bf16(v0[2] * __builtin_amdgcn_rcpf(bf_lo(g.y)), v0[3] * __builtin_amdgcn_rcpf(bf_hi(g.y)));
;                     w.z = cvt_pk_bf16(v1[0] * __builtin_amdgcn_rcpf(bf_lo(g.z)), v1[1] * __builtin_amdgcn_rcpf(bf_hi(g.z)));
;                     w.w = cvt_pk_bf16(v1[2] * __builtin_amdgcn_rcpf(bf_lo(g.w)), v1[3] * __builtin_amdgcn_rcpf(bf_hi(g.w)));
;                     *(u32x4*)(mb + (rl * 1024u + cl) * 2u) = w; } }
;             asm volatile("" : "+v"(rl0), "+v"(cl0) :: "memory"); }
.LBB0_57:
	v_mov_b32_e32 v132, v212
	s_lshl_b32 s61, s6, 10
	v_readfirstlane_b32 s31, v132
	s_lshl_b32 s62, s60, 3
	s_ashr_i32 s36, s31, 6
	s_add_i32 s61, s61, s62
	s_nop 0
	s_add_i32 s62, s61, 0x2000
	s_ashr_i32 s63, s62, 31
	s_lshl_b64 s[62:63], s[62:63], 14
	s_add_u32 s62, s33, s62
	s_addc_u32 s63, s37, s63
	s_ashr_i32 s61, s60, 31
	s_lshl_b64 s[60:61], s[60:61], 19
	s_add_u32 s64, s89, s60
	s_addc_u32 s65, s3, s61
	s_lshl_b32 s60, s6, 8
	s_ashr_i32 s61, s60, 31
	s_lshl_b64 s[60:61], s[60:61], 1
	s_add_u32 s60, s64, s60
	s_addc_u32 s61, s65, s61
	s_ashr_i32 s6, s31, 2
	s_andn2_b32 s6, s6, 63
	v_and_or_b32 v158, v132, 15, s6
	s_lshl_b32 s6, s36, 5
	v_lshlrev_b32_e32 v96, 4, v132
	s_and_b32 s6, s6, 0x60
	v_lshrrev_b32_e32 v132, 1, v132
	v_and_b32_e32 v96, 0x3f0, v96
	v_and_b32_e32 v171, 15, v212
	v_lshlrev_b32_e32 v171, 9, v171
	v_and_b32_e32 v172, 0x30, v212
	v_or_b32_e32 v171, v171, v172
	v_and_b32_e32 v172, 0xc0, v212
	v_lshl_or_b32 v171, v172, 1, v171
	v_and_b32_e32 v172, 0x100, v212
	v_lshl_or_b32 v170, v172, 7, v171
	v_and_or_b32 v159, v132, 24, s6
	v_mov_b32_e32 v171, v170
	global_load_dwordx4 v[160:163], v171, s[62:63]
	v_add_u32_e32 v171, 0x40, v170
	global_load_dwordx4 v[164:167], v171, s[62:63]
	v_add_u32_e32 v171, 0x2000, v170
	global_load_dwordx4 v[152:155], v171, s[62:63]
	v_add_u32_e32 v171, 0x2040, v170
	global_load_dwordx4 v[148:151], v171, s[62:63]
	v_lshl_add_u64 v[98:99], s[62:63], 0, v[96:97]
	s_movk_i32 s6, 0x1000
	v_add_co_u32_e32 v132, vcc, s6, v98
	s_movk_i32 s6, 0x2000
	s_nop 0
	v_addc_co_u32_e32 v133, vcc, 0, v99, vcc
	v_add_co_u32_e32 v156, vcc, s6, v98
	v_lshlrev_b32_e32 v96, 1, v159
	s_nop 0
	v_addc_co_u32_e32 v157, vcc, 0, v99, vcc
	v_add_u32_e32 v171, 0x4000, v170
	global_load_dwordx4 v[144:147], v171, s[62:63]
	v_add_u32_e32 v171, 0x4040, v170
	global_load_dwordx4 v[140:143], v171, s[62:63]
	v_add_u32_e32 v171, 0x6000, v170
	global_load_dwordx4 v[136:139], v171, s[62:63]
	s_nop 0
	v_add_u32_e32 v171, 0x6040, v170
	global_load_dwordx4 v[132:135], v171, s[62:63]
	v_lshl_add_u32 v96, v158, 11, v96
	s_movk_i32 s6, 0x3000
	s_waitcnt vmcnt(0)
	v_lshlrev_b32_e32 v168, 16, v160
	v_and_b32_e32 v160, 0xffff0000, v160
	v_rcp_f32_e32 v168, v168
	v_rcp_f32_e32 v169, v160
	s_nop 0
	v_pk_mul_f32 v[128:129], v[128:129], v[168:169]
	s_nop 0
	v_cvt_pk_bf16_f32 v128, v128, v129
	v_lshlrev_b32_e32 v129, 16, v161
	v_rcp_f32_e32 v160, v129
	v_and_b32_e32 v129, 0xffff0000, v161
	v_rcp_f32_e32 v161, v129
	s_nop 0
	v_pk_mul_f32 v[130:131], v[130:131], v[160:161]
	s_nop 0
	v_cvt_pk_bf16_f32 v129, v130, v131
	v_lshlrev_b32_e32 v130, 16, v162
	v_and_b32_e32 v131, 0xffff0000, v162
	v_rcp_f32_e32 v130, v130
	v_rcp_f32_e32 v131, v131
	s_nop 0
	v_pk_mul_f32 v[120:121], v[120:121], v[130:131]
	s_nop 0
	v_cvt_pk_bf16_f32 v130, v120, v121
	v_lshlrev_b32_e32 v120, 16, v163
	v_and_b32_e32 v121, 0xffff0000, v163
	v_rcp_f32_e32 v120, v120
	v_rcp_f32_e32 v121, v121
	s_nop 0
	v_pk_mul_f32 v[120:121], v[122:123], v[120:121]
	s_nop 0
	v_cvt_pk_bf16_f32 v131, v120, v121
	v_lshlrev_b32_e32 v120, 16, v164
	v_and_b32_e32 v121, 0xffff0000, v164
	v_rcp_f32_e32 v120, v120
	v_rcp_f32_e32 v121, v121
	global_store_dwordx4 v96, v[128:131], s[60:61]
	v_pk_mul_f32 v[120:121], v[124:125], v[120:121]
	s_nop 0
	v_cvt_pk_bf16_f32 v120, v120, v121
	v_lshlrev_b32_e32 v121, 16, v165
	v_rcp_f32_e32 v122, v121
	v_and_b32_e32 v121, 0xffff0000, v165
	v_rcp_f32_e32 v123, v121
	s_nop 0
	v_pk_mul_f32 v[122:123], v[126:127], v[122:123]
	s_nop 0
	v_cvt_pk_bf16_f32 v121, v122, v123
	v_lshlrev_b32_e32 v122, 16, v166
	v_and_b32_e32 v123, 0xffff0000, v166
	v_rcp_f32_e32 v122, v122
	v_rcp_f32_e32 v123, v123
	s_nop 0
	v_pk_mul_f32 v[116:117], v[116:117], v[122:123]
	s_nop 0
	v_cvt_pk_bf16_f32 v122, v116, v117
	v_lshlrev_b32_e32 v116, 16, v167
	v_and_b32_e32 v117, 0xffff0000, v167
	v_rcp_f32_e32 v116, v116
	v_rcp_f32_e32 v117, v117
	s_nop 0
	v_pk_mul_f32 v[116:117], v[118:119], v[116:117]
	s_nop 0
	v_cvt_pk_bf16_f32 v123, v116, v117
	v_add_u32_e32 v116, 0x100, v96
	global_store_dwordx4 v116, v[120:123], s[60:61]
	v_lshlrev_b32_e32 v116, 16, v152
	v_and_b32_e32 v117, 0xffff0000, v152
	v_rcp_f32_e32 v116, v116
	v_rcp_f32_e32 v117, v117
	v_add_u32_e32 v118, 0x8000, v96
	v_pk_mul_f32 v[112:113], v[112:113], v[116:117]
	s_nop 0
	v_cvt_pk_bf16_f32 v112, v112, v113
	v_lshlrev_b32_e32 v113, 16, v153
	v_rcp_f32_e32 v116, v113
	v_and_b32_e32 v113, 0xffff0000, v153
	v_rcp_f32_e32 v117, v113
	s_nop 0
	v_pk_mul_f32 v[114:115], v[114:115], v[116:117]
	s_nop 0
	v_cvt_pk_bf16_f32 v113, v114, v115
	v_lshlrev_b32_e32 v114, 16, v154
	v_and_b32_e32 v115, 0xffff0000, v154
	v_rcp_f32_e32 v114, v114
	v_rcp_f32_e32 v115, v115
	s_nop 0
	v_pk_mul_f32 v[108:109], v[108:109], v[114:115]
	s_nop 0
	v_cvt_pk_bf16_f32 v114, v108, v109
	v_lshlrev_b32_e32 v108, 16, v155
	v_and_b32_e32 v109, 0xffff0000, v155
	v_rcp_f32_e32 v108, v108
	v_rcp_f32_e32 v109, v109
	s_nop 0
	v_pk_mul_f32 v[108:109], v[110:111], v[108:109]
	s_nop 0
	v_cvt_pk_bf16_f32 v115, v108, v109
	v_lshlrev_b32_e32 v108, 16, v148
	v_and_b32_e32 v109, 0xffff0000, v148
	v_rcp_f32_e32 v108, v108
	v_rcp_f32_e32 v109, v109
	global_store_dwordx4 v118, v[112:115], s[60:61]
	v_pk_mul_f32 v[104:105], v[104:105], v[108:109]
	s_nop 0
	v_cvt_pk_bf16_f32 v104, v104, v105
	v_lshlrev_b32_e32 v105, 16, v149
	v_rcp_f32_e32 v108, v105
	v_and_b32_e32 v105, 0xffff0000, v149
	v_rcp_f32_e32 v109, v105
	s_nop 0
	v_pk_mul_f32 v[106:107], v[106:107], v[108:109]
	s_nop 0
	v_cvt_pk_bf16_f32 v105, v106, v107
	v_lshlrev_b32_e32 v106, 16, v150
	v_and_b32_e32 v107, 0xffff0000, v150
	v_rcp_f32_e32 v106, v106
	v_rcp_f32_e32 v107, v107
	s_nop 0
	v_pk_mul_f32 v[100:101], v[100:101], v[106:107]
; __device__ __forceinline__ float bf_lo(unsigned w) { return __uint_as_float(w << 16); }
; __device__ __forceinline__ float bf_hi(unsigned w) { return __uint_as_float(w & 0xffff0000u); }
; __device__ __forceinline__ unsigned cvt_pk_bf16(float lo, float hi) { f32x2_t v = {lo, hi}; bf16x2_t b = __builtin_convertvector(v, bf16x2_t); return __builtin_bit_cast(unsigned, b); }
; #define EPI_LANE() int t__ = threadIdx.x; asm volatile("" : "+v"(t__)); const int wid__ = __builtin_amdgcn_readfirstlane(t__ >> 6); wr = wid__ >> 2; wc = wid__ & 3; fr = t__ & 15; fq = (t__ & 63) >> 4
;     __device__ __forceinline__ void operator()(const f32x4 (&acc)[2][2][4][2], const Unit& u, int wr, int wc, int fr, int fq) const {
;         EPI_LANE();
;         const char* g_b = gbase(2, u, wid__) + (t__ & 63) * 16; char* mb = (char*)(Mg + (size_t)u.pm * BM * 1024 + u.pn * BM);
;         unsigned rl0 = (unsigned)(wr * 64 + fr), cl0 = (unsigned)(wc * 32 + 8 * fq); asm volatile("" : "+v"(rl0), "+v"(cl0));
; #pragma unroll
;         for (int ai = 0; ai < 2; ++ai) {
;             u32x4 gv[4][2];
; #pragma unroll
;             for (int m = 0; m < 4; ++m)
; #pragma unroll
;                 for (int bj = 0; bj < 2; ++bj) gv[m][bj] = *(const u32x4*)(g_b + ((ai * 4 + m) * 2 + bj) * 1024);
; #pragma unroll
;             for (int m = 0; m < 4; ++m) { const unsigned rl = rl0 + (unsigned)(ai * HALF + m * 16);
; #pragma unroll
;                 for (int bj = 0; bj < 2; ++bj) { const unsigned cl = cl0 + (unsigned)(bj * HALF);
;                     const u32x4 g = gv[m][bj];
;                     const f32x4 v0 = acc[ai][bj][m][0], v1 = acc[ai][bj][m][1];
;                     u32x4 w;
;                     w.x = cvt_pk_bf16(v0[0] * __builtin_amdgcn_rcpf(bf_lo(g.x)), v0[1] * __builtin_amdgcn_rcpf(bf_hi(g.x)));
;                     w.y = cvt_pk_bf16(v0[2] * __builtin_amdgcn_rcpf(bf_lo(g.y)), v0[3] * __builtin_amdgcn_rcpf(bf_hi(g.y)));
;                     w.z = cvt_pk_bf16(v1[0] * __builtin_amdgcn_rcpf(bf_lo(g.z)), v1[1] * __builtin_amdgcn_rcpf(bf_hi(g.z)));
;                     w.w = cvt_pk_bf16(v1[2] * __builtin_amdgcn_rcpf(bf_lo(g.w)), v1[3] * __builtin_amdgcn_rcpf(bf_hi(g.w)));
;                     *(u32x4*)(mb + (rl * 1024u + cl) * 2u) = w; } }
;             asm volatile("" : "+v"(rl0), "+v"(cl0) :: "memory"); }
	s_nop 0
	v_cvt_pk_bf16_f32 v106, v100, v101
	v_lshlrev_b32_e32 v100, 16, v151
	v_and_b32_e32 v101, 0xffff0000, v151
	v_rcp_f32_e32 v100, v100
	v_rcp_f32_e32 v101, v101
	s_nop 0
	v_pk_mul_f32 v[100:101], v[102:103], v[100:101]
	s_nop 0
	v_cvt_pk_bf16_f32 v107, v100, v101
	v_add_u32_e32 v100, 0x8100, v96
	global_store_dwordx4 v100, v[104:107], s[60:61]
	v_lshlrev_b32_e32 v100, 16, v144
	v_and_b32_e32 v101, 0xffff0000, v144
	v_rcp_f32_e32 v100, v100
	v_rcp_f32_e32 v101, v101
	v_add_u32_e32 v102, 0x10000, v96
	v_pk_mul_f32 v[92:93], v[92:93], v[100:101]
	s_nop 0
	v_cvt_pk_bf16_f32 v92, v92, v93
	v_lshlrev_b32_e32 v93, 16, v145
	v_rcp_f32_e32 v100, v93
	v_and_b32_e32 v93, 0xffff0000, v145
	v_rcp_f32_e32 v101, v93
	s_nop 0
	v_pk_mul_f32 v[94:95], v[94:95], v[100:101]
	s_nop 0
	v_cvt_pk_bf16_f32 v93, v94, v95
	v_lshlrev_b32_e32 v94, 16, v146
	v_and_b32_e32 v95, 0xffff0000, v146
	v_rcp_f32_e32 v94, v94
	v_rcp_f32_e32 v95, v95
	s_nop 0
	v_pk_mul_f32 v[88:89], v[88:89], v[94:95]
	s_nop 0
	v_cvt_pk_bf16_f32 v94, v88, v89
	v_lshlrev_b32_e32 v88, 16, v147
	v_and_b32_e32 v89, 0xffff0000, v147
	v_rcp_f32_e32 v88, v88
	v_rcp_f32_e32 v89, v89
	s_nop 0
	v_pk_mul_f32 v[88:89], v[90:91], v[88:89]
	s_nop 0
	v_cvt_pk_bf16_f32 v95, v88, v89
	v_lshlrev_b32_e32 v88, 16, v140
	v_and_b32_e32 v89, 0xffff0000, v140
	v_rcp_f32_e32 v88, v88
	v_rcp_f32_e32 v89, v89
	global_store_dwordx4 v102, v[92:95], s[60:61]
	v_pk_mul_f32 v[84:85], v[84:85], v[88:89]
	s_nop 0
	v_cvt_pk_bf16_f32 v84, v84, v85
	v_lshlrev_b32_e32 v85, 16, v141
	v_rcp_f32_e32 v88, v85
	v_and_b32_e32 v85, 0xffff0000, v141
	v_rcp_f32_e32 v89, v85
	s_nop 0
	v_pk_mul_f32 v[86:87], v[86:87], v[88:89]
	s_nop 0
	v_cvt_pk_bf16_f32 v85, v86, v87
	v_lshlrev_b32_e32 v86, 16, v142
	v_and_b32_e32 v87, 0xffff0000, v142
	v_rcp_f32_e32 v86, v86
	v_rcp_f32_e32 v87, v87
	s_nop 0
	v_pk_mul_f32 v[80:81], v[80:81], v[86:87]
	s_nop 0
	v_cvt_pk_bf16_f32 v86, v80, v81
	v_lshlrev_b32_e32 v80, 16, v143
	v_and_b32_e32 v81, 0xffff0000, v143
	v_rcp_f32_e32 v80, v80
	v_rcp_f32_e32 v81, v81
	s_nop 0
	v_pk_mul_f32 v[80:81], v[82:83], v[80:81]
	s_nop 0
	v_cvt_pk_bf16_f32 v87, v80, v81
	v_add_u32_e32 v80, 0x10100, v96
	global_store_dwordx4 v80, v[84:87], s[60:61]
	v_lshlrev_b32_e32 v80, 16, v136
	v_and_b32_e32 v81, 0xffff0000, v136
	v_rcp_f32_e32 v80, v80
	v_rcp_f32_e32 v81, v81
	v_add_u32_e32 v82, 0x18000, v96
	v_pk_mul_f32 v[76:77], v[76:77], v[80:81]
	s_nop 0
	v_cvt_pk_bf16_f32 v76, v76, v77
	v_lshlrev_b32_e32 v77, 16, v137
	v_rcp_f32_e32 v80, v77
	v_and_b32_e32 v77, 0xffff0000, v137
	v_rcp_f32_e32 v81, v77
	s_nop 0
	v_pk_mul_f32 v[78:79], v[78:79], v[80:81]
	s_nop 0
	v_cvt_pk_bf16_f32 v77, v78, v79
	v_lshlrev_b32_e32 v78, 16, v138
	v_and_b32_e32 v79, 0xffff0000, v138
	v_rcp_f32_e32 v78, v78
	v_rcp_f32_e32 v79, v79
	s_nop 0
	v_pk_mul_f32 v[72:73], v[72:73], v[78:79]
	s_nop 0
	v_cvt_pk_bf16_f32 v78, v72, v73
	v_lshlrev_b32_e32 v72, 16, v139
	v_and_b32_e32 v73, 0xffff0000, v139
	v_rcp_f32_e32 v72, v72
	v_rcp_f32_e32 v73, v73
	s_nop 0
	v_pk_mul_f32 v[72:73], v[74:75], v[72:73]
	s_nop 0
	v_cvt_pk_bf16_f32 v79, v72, v73
	v_lshlrev_b32_e32 v72, 16, v132
	v_and_b32_e32 v73, 0xffff0000, v132
	v_rcp_f32_e32 v72, v72
	v_rcp_f32_e32 v73, v73
	global_store_dwordx4 v82, v[76:79], s[60:61]
	v_pk_mul_f32 v[68:69], v[68:69], v[72:73]
	s_nop 0
	v_cvt_pk_bf16_f32 v68, v68, v69
	v_lshlrev_b32_e32 v69, 16, v133
	v_rcp_f32_e32 v72, v69
	v_and_b32_e32 v69, 0xffff0000, v133
	v_rcp_f32_e32 v73, v69
	s_nop 0
	v_pk_mul_f32 v[70:71], v[70:71], v[72:73]
	s_nop 0
	v_cvt_pk_bf16_f32 v69, v70, v71
	v_lshlrev_b32_e32 v70, 16, v134
	v_and_b32_e32 v71, 0xffff0000, v134
	v_rcp_f32_e32 v70, v70
	v_rcp_f32_e32 v71, v71
	s_nop 0
	v_pk_mul_f32 v[64:65], v[64:65], v[70:71]
	s_nop 0
	v_cvt_pk_bf16_f32 v70, v64, v65
	v_lshlrev_b32_e32 v64, 16, v135
	v_and_b32_e32 v65, 0xffff0000, v135
	v_rcp_f32_e32 v64, v64
	v_rcp_f32_e32 v65, v65
	s_nop 0
	v_pk_mul_f32 v[64:65], v[66:67], v[64:65]
	s_nop 0
	v_cvt_pk_bf16_f32 v71, v64, v65
	v_add_u32_e32 v64, 0x18100, v96
	global_store_dwordx4 v64, v[68:71], s[60:61]
	v_add_u32_e32 v171, 0x10000, v170
	global_load_dwordx4 v[90:93], v171, s[62:63]
	v_add_u32_e32 v171, 0x10040, v170
	global_load_dwordx4 v[100:103], v171, s[62:63]
	v_add_u32_e32 v171, 0x12000, v170
	global_load_dwordx4 v[84:87], v171, s[62:63]
	v_add_u32_e32 v171, 0x12040, v170
	global_load_dwordx4 v[80:83], v171, s[62:63]
	v_add_co_u32_e32 v64, vcc, s6, v98
	v_lshlrev_b32_e32 v88, 11, v158
	s_nop 0
	v_addc_co_u32_e32 v65, vcc, 0, v99, vcc
	v_add_u32_e32 v171, 0x14000, v170
	global_load_dwordx4 v[76:79], v171, s[62:63]
	v_add_u32_e32 v171, 0x14040, v170
	global_load_dwordx4 v[72:75], v171, s[62:63]
	v_add_u32_e32 v171, 0x16000, v170
	global_load_dwordx4 v[68:71], v171, s[62:63]
	s_nop 0
	v_add_u32_e32 v171, 0x16040, v170
	global_load_dwordx4 v[64:67], v171, s[62:63]
	v_lshl_add_u32 v88, v159, 1, v88
	v_add_u32_e32 v89, 0x40000, v88
	s_and_b64 vcc, exec, s[38:39]
	s_waitcnt vmcnt(0)
; __device__ __forceinline__ float bf_lo(unsigned w) { return __uint_as_float(w << 16); }
; __device__ __forceinline__ float bf_hi(unsigned w) { return __uint_as_float(w & 0xffff0000u); }
; __device__ __forceinline__ unsigned cvt_pk_bf16(float lo, float hi) { f32x2_t v = {lo, hi}; bf16x2_t b = __builtin_convertvector(v, bf16x2_t); return __builtin_bit_cast(unsigned, b); }
;     __device__ __forceinline__ void operator()(const f32x4 (&acc)[2][2][4][2], const Unit& u, int wr, int wc, int fr, int fq) const {
;     ...
;             for (int m = 0; m < 4; ++m) { const unsigned rl = rl0 + (unsigned)(ai * HALF + m * 16);
; #pragma unroll
;                 for (int bj = 0; bj < 2; ++bj) { const unsigned cl = cl0 + (unsigned)(bj * HALF);
;                     const u32x4 g = gv[m][bj];
;                     const f32x4 v0 = acc[ai][bj][m][0], v1 = acc[ai][bj][m][1];
;                     u32x4 w;
;                     w.x = cvt_pk_bf16(v0[0] * __builtin_amdgcn_rcpf(bf_lo(g.x)), v0[1] * __builtin_amdgcn_rcpf(bf_hi(g.x)));
;                     w.y = cvt_pk_bf16(v0[2] * __builtin_amdgcn_rcpf(bf_lo(g.y)), v0[3] * __builtin_amdgcn_rcpf(bf_hi(g.y)));
;                     w.z = cvt_pk_bf16(v1[0] * __builtin_amdgcn_rcpf(bf_lo(g.z)), v1[1] * __builtin_amdgcn_rcpf(bf_hi(g.z)));
;                     w.w = cvt_pk_bf16(v1[2] * __builtin_amdgcn_rcpf(bf_lo(g.w)), v1[3] * __builtin_amdgcn_rcpf(bf_hi(g.w)));
;                     *(u32x4*)(mb + (rl * 1024u + cl) * 2u) = w; } }
;             asm volatile("" : "+v"(rl0), "+v"(cl0) :: "memory"); }
	v_lshlrev_b32_e32 v94, 16, v90
	v_and_b32_e32 v90, 0xffff0000, v90
	v_rcp_f32_e32 v94, v94
	v_rcp_f32_e32 v95, v90
	s_nop 0
	v_pk_mul_f32 v[60:61], v[60:61], v[94:95]
	s_nop 0
	v_cvt_pk_bf16_f32 v60, v60, v61
	v_lshlrev_b32_e32 v61, 16, v91
	v_rcp_f32_e32 v90, v61
	v_and_b32_e32 v61, 0xffff0000, v91
	v_rcp_f32_e32 v91, v61
	s_nop 0
	v_pk_mul_f32 v[62:63], v[62:63], v[90:91]
	s_nop 0
	v_cvt_pk_bf16_f32 v61, v62, v63
	v_lshlrev_b32_e32 v62, 16, v92
	v_and_b32_e32 v63, 0xffff0000, v92
	v_rcp_f32_e32 v62, v62
	v_rcp_f32_e32 v63, v63
	s_nop 0
	v_pk_mul_f32 v[56:57], v[56:57], v[62:63]
	s_nop 0
	v_cvt_pk_bf16_f32 v62, v56, v57
	v_lshlrev_b32_e32 v56, 16, v93
	v_and_b32_e32 v57, 0xffff0000, v93
	v_rcp_f32_e32 v56, v56
	v_rcp_f32_e32 v57, v57
	s_nop 0
	v_pk_mul_f32 v[56:57], v[58:59], v[56:57]
	s_nop 0
	v_cvt_pk_bf16_f32 v63, v56, v57
	v_lshlrev_b32_e32 v56, 16, v100
	v_and_b32_e32 v57, 0xffff0000, v100
	v_rcp_f32_e32 v56, v56
	v_rcp_f32_e32 v57, v57
	global_store_dwordx4 v89, v[60:63], s[60:61]
	v_pk_mul_f32 v[52:53], v[52:53], v[56:57]
	s_nop 0
	v_cvt_pk_bf16_f32 v52, v52, v53
	v_lshlrev_b32_e32 v53, 16, v101
	v_rcp_f32_e32 v56, v53
	v_and_b32_e32 v53, 0xffff0000, v101
	v_rcp_f32_e32 v57, v53
	s_nop 0
	v_pk_mul_f32 v[54:55], v[54:55], v[56:57]
	s_nop 0
	v_cvt_pk_bf16_f32 v53, v54, v55
	v_lshlrev_b32_e32 v54, 16, v102
	v_and_b32_e32 v55, 0xffff0000, v102
	v_rcp_f32_e32 v54, v54
	v_rcp_f32_e32 v55, v55
	s_nop 0
	v_pk_mul_f32 v[48:49], v[48:49], v[54:55]
	s_nop 0
	v_cvt_pk_bf16_f32 v54, v48, v49
	v_lshlrev_b32_e32 v48, 16, v103
	v_and_b32_e32 v49, 0xffff0000, v103
	v_rcp_f32_e32 v48, v48
	v_rcp_f32_e32 v49, v49
	s_nop 0
	v_pk_mul_f32 v[48:49], v[50:51], v[48:49]
	s_nop 0
	v_cvt_pk_bf16_f32 v55, v48, v49
	v_add_u32_e32 v48, 0x40100, v88
	global_store_dwordx4 v48, v[52:55], s[60:61]
	v_lshlrev_b32_e32 v48, 16, v84
	v_and_b32_e32 v49, 0xffff0000, v84
	v_rcp_f32_e32 v48, v48
	v_rcp_f32_e32 v49, v49
	v_add_u32_e32 v50, 0x48000, v88
	v_pk_mul_f32 v[44:45], v[44:45], v[48:49]
	s_nop 0
	v_cvt_pk_bf16_f32 v44, v44, v45
	v_lshlrev_b32_e32 v45, 16, v85
	v_rcp_f32_e32 v48, v45
	v_and_b32_e32 v45, 0xffff0000, v85
	v_rcp_f32_e32 v49, v45
	s_nop 0
	v_pk_mul_f32 v[46:47], v[46:47], v[48:49]
	s_nop 0
	v_cvt_pk_bf16_f32 v45, v46, v47
	v_lshlrev_b32_e32 v46, 16, v86
	v_and_b32_e32 v47, 0xffff0000, v86
	v_rcp_f32_e32 v46, v46
	v_rcp_f32_e32 v47, v47
	s_nop 0
	v_pk_mul_f32 v[40:41], v[40:41], v[46:47]
	s_nop 0
	v_cvt_pk_bf16_f32 v46, v40, v41
	v_lshlrev_b32_e32 v40, 16, v87
	v_and_b32_e32 v41, 0xffff0000, v87
	v_rcp_f32_e32 v40, v40
	v_rcp_f32_e32 v41, v41
	s_nop 0
	v_pk_mul_f32 v[40:41], v[42:43], v[40:41]
	s_nop 0
	v_cvt_pk_bf16_f32 v47, v40, v41
	v_lshlrev_b32_e32 v40, 16, v80
	v_and_b32_e32 v41, 0xffff0000, v80
	v_rcp_f32_e32 v40, v40
	v_rcp_f32_e32 v41, v41
	global_store_dwordx4 v50, v[44:47], s[60:61]
	v_pk_mul_f32 v[36:37], v[36:37], v[40:41]
	s_nop 0
	v_cvt_pk_bf16_f32 v36, v36, v37
	v_lshlrev_b32_e32 v37, 16, v81
	v_rcp_f32_e32 v40, v37
	v_and_b32_e32 v37, 0xffff0000, v81
	v_rcp_f32_e32 v41, v37
	s_nop 0
	v_pk_mul_f32 v[38:39], v[38:39], v[40:41]
	s_nop 0
	v_cvt_pk_bf16_f32 v37, v38, v39
	v_lshlrev_b32_e32 v38, 16, v82
	v_and_b32_e32 v39, 0xffff0000, v82
	v_rcp_f32_e32 v38, v38
	v_rcp_f32_e32 v39, v39
	s_nop 0
	v_pk_mul_f32 v[32:33], v[32:33], v[38:39]
	s_nop 0
	v_cvt_pk_bf16_f32 v38, v32, v33
	v_lshlrev_b32_e32 v32, 16, v83
	v_and_b32_e32 v33, 0xffff0000, v83
	v_rcp_f32_e32 v32, v32
	v_rcp_f32_e32 v33, v33
	s_nop 0
	v_pk_mul_f32 v[32:33], v[34:35], v[32:33]
	s_nop 0
	v_cvt_pk_bf16_f32 v39, v32, v33
	v_add_u32_e32 v32, 0x48100, v88
	global_store_dwordx4 v32, v[36:39], s[60:61]
	v_lshlrev_b32_e32 v32, 16, v76
; __device__ __forceinline__ float bf_lo(unsigned w) { return __uint_as_float(w << 16); }
; __device__ __forceinline__ float bf_hi(unsigned w) { return __uint_as_float(w & 0xffff0000u); }
; __device__ __forceinline__ unsigned cvt_pk_bf16(float lo, float hi) { f32x2_t v = {lo, hi}; bf16x2_t b = __builtin_convertvector(v, bf16x2_t); return __builtin_bit_cast(unsigned, b); }
;     __device__ __forceinline__ void operator()(const f32x4 (&acc)[2][2][4][2], const Unit& u, int wr, int wc, int fr, int fq) const {
;     ...
;             for (int m = 0; m < 4; ++m) { const unsigned rl = rl0 + (unsigned)(ai * HALF + m * 16);
; #pragma unroll
;                 for (int bj = 0; bj < 2; ++bj) { const unsigned cl = cl0 + (unsigned)(bj * HALF);
;                     const u32x4 g = gv[m][bj];
;                     const f32x4 v0 = acc[ai][bj][m][0], v1 = acc[ai][bj][m][1];
;                     u32x4 w;
;                     w.x = cvt_pk_bf16(v0[0] * __builtin_amdgcn_rcpf(bf_lo(g.x)), v0[1] * __builtin_amdgcn_rcpf(bf_hi(g.x)));
;                     w.y = cvt_pk_bf16(v0[2] * __builtin_amdgcn_rcpf(bf_lo(g.y)), v0[3] * __builtin_amdgcn_rcpf(bf_hi(g.y)));
;                     w.z = cvt_pk_bf16(v1[0] * __builtin_amdgcn_rcpf(bf_lo(g.z)), v1[1] * __builtin_amdgcn_rcpf(bf_hi(g.z)));
;                     w.w = cvt_pk_bf16(v1[2] * __builtin_amdgcn_rcpf(bf_lo(g.w)), v1[3] * __builtin_amdgcn_rcpf(bf_hi(g.w)));
;                     *(u32x4*)(mb + (rl * 1024u + cl) * 2u) = w; } }
;             asm volatile("" : "+v"(rl0), "+v"(cl0) :: "memory"); }
	v_and_b32_e32 v33, 0xffff0000, v76
	v_rcp_f32_e32 v32, v32
	v_rcp_f32_e32 v33, v33
	v_add_u32_e32 v34, 0x50000, v88
	v_pk_mul_f32 v[28:29], v[28:29], v[32:33]
	s_nop 0
	v_cvt_pk_bf16_f32 v28, v28, v29
	v_lshlrev_b32_e32 v29, 16, v77
	v_rcp_f32_e32 v32, v29
	v_and_b32_e32 v29, 0xffff0000, v77
	v_rcp_f32_e32 v33, v29
	s_nop 0
	v_pk_mul_f32 v[30:31], v[30:31], v[32:33]
	s_nop 0
	v_cvt_pk_bf16_f32 v29, v30, v31
	v_lshlrev_b32_e32 v30, 16, v78
	v_and_b32_e32 v31, 0xffff0000, v78
	v_rcp_f32_e32 v30, v30
	v_rcp_f32_e32 v31, v31
	s_nop 0
	v_pk_mul_f32 v[24:25], v[24:25], v[30:31]
	s_nop 0
	v_cvt_pk_bf16_f32 v30, v24, v25
	v_lshlrev_b32_e32 v24, 16, v79
	v_and_b32_e32 v25, 0xffff0000, v79
	v_rcp_f32_e32 v24, v24
	v_rcp_f32_e32 v25, v25
	s_nop 0
	v_pk_mul_f32 v[24:25], v[26:27], v[24:25]
	s_nop 0
	v_cvt_pk_bf16_f32 v31, v24, v25
	v_lshlrev_b32_e32 v24, 16, v72
	v_and_b32_e32 v25, 0xffff0000, v72
	v_rcp_f32_e32 v24, v24
	v_rcp_f32_e32 v25, v25
	global_store_dwordx4 v34, v[28:31], s[60:61]
	v_pk_mul_f32 v[20:21], v[20:21], v[24:25]
	s_nop 0
	v_cvt_pk_bf16_f32 v20, v20, v21
	v_lshlrev_b32_e32 v21, 16, v73
	v_rcp_f32_e32 v24, v21
	v_and_b32_e32 v21, 0xffff0000, v73
	v_rcp_f32_e32 v25, v21
	s_nop 0
	v_pk_mul_f32 v[22:23], v[22:23], v[24:25]
	s_nop 0
	v_cvt_pk_bf16_f32 v21, v22, v23
	v_lshlrev_b32_e32 v22, 16, v74
	v_and_b32_e32 v23, 0xffff0000, v74
	v_rcp_f32_e32 v22, v22
	v_rcp_f32_e32 v23, v23
	s_nop 0
	v_pk_mul_f32 v[12:13], v[12:13], v[22:23]
	s_nop 0
	v_cvt_pk_bf16_f32 v22, v12, v13
	v_lshlrev_b32_e32 v12, 16, v75
	v_and_b32_e32 v13, 0xffff0000, v75
	v_rcp_f32_e32 v12, v12
	v_rcp_f32_e32 v13, v13
	s_nop 0
	v_pk_mul_f32 v[12:13], v[14:15], v[12:13]
	s_nop 0
	v_cvt_pk_bf16_f32 v23, v12, v13
	v_add_u32_e32 v12, 0x50100, v88
	global_store_dwordx4 v12, v[20:23], s[60:61]
	v_lshlrev_b32_e32 v12, 16, v68
	v_and_b32_e32 v13, 0xffff0000, v68
	v_rcp_f32_e32 v12, v12
	v_rcp_f32_e32 v13, v13
	v_add_u32_e32 v20, 0x58000, v88
	v_pk_mul_f32 v[12:13], v[16:17], v[12:13]
	s_nop 0
	v_cvt_pk_bf16_f32 v12, v12, v13
	v_lshlrev_b32_e32 v13, 16, v69
	v_rcp_f32_e32 v14, v13
	v_and_b32_e32 v13, 0xffff0000, v69
	v_rcp_f32_e32 v15, v13
	s_nop 0
	v_pk_mul_f32 v[14:15], v[18:19], v[14:15]
	s_nop 0
	v_cvt_pk_bf16_f32 v13, v14, v15
	v_lshlrev_b32_e32 v14, 16, v70
	v_and_b32_e32 v15, 0xffff0000, v70
	v_rcp_f32_e32 v14, v14
	v_rcp_f32_e32 v15, v15
	s_nop 0
	v_pk_mul_f32 v[8:9], v[8:9], v[14:15]
	s_nop 0
	v_cvt_pk_bf16_f32 v14, v8, v9
	v_lshlrev_b32_e32 v8, 16, v71
	v_and_b32_e32 v9, 0xffff0000, v71
	v_rcp_f32_e32 v8, v8
	v_rcp_f32_e32 v9, v9
	s_nop 0
	v_pk_mul_f32 v[8:9], v[10:11], v[8:9]
	s_nop 0
	v_cvt_pk_bf16_f32 v15, v8, v9
	v_lshlrev_b32_e32 v8, 16, v64
	v_and_b32_e32 v9, 0xffff0000, v64
	v_rcp_f32_e32 v8, v8
	v_rcp_f32_e32 v9, v9
	global_store_dwordx4 v20, v[12:15], s[60:61]
	v_pk_mul_f32 v[4:5], v[4:5], v[8:9]
	s_nop 0
	v_cvt_pk_bf16_f32 v4, v4, v5
	v_lshlrev_b32_e32 v5, 16, v65
	v_rcp_f32_e32 v8, v5
	v_and_b32_e32 v5, 0xffff0000, v65
	v_rcp_f32_e32 v9, v5
	s_nop 0
	v_pk_mul_f32 v[6:7], v[6:7], v[8:9]
	s_nop 0
	v_cvt_pk_bf16_f32 v5, v6, v7
	v_lshlrev_b32_e32 v6, 16, v66
	v_and_b32_e32 v7, 0xffff0000, v66
	v_rcp_f32_e32 v6, v6
	v_rcp_f32_e32 v7, v7
	s_nop 0
	v_pk_mul_f32 v[0:1], v[0:1], v[6:7]
	s_nop 0
	v_cvt_pk_bf16_f32 v6, v0, v1
	v_lshlrev_b32_e32 v0, 16, v67
	v_and_b32_e32 v1, 0xffff0000, v67
	v_rcp_f32_e32 v0, v0
	v_rcp_f32_e32 v1, v1
	s_nop 0
	v_pk_mul_f32 v[0:1], v[2:3], v[0:1]
	s_nop 0
	v_cvt_pk_bf16_f32 v7, v0, v1
	v_add_u32_e32 v0, 0x58100, v88
	global_store_dwordx4 v0, v[4:7], s[60:61]
	s_mov_b64 s[60:61], -1
	s_cbranch_vccnz .LBB0_35
	s_andn2_b64 vcc, exec, s[46:47]
	s_cbranch_vccnz .LBB0_34
	s_barrier
	s_branch .LBB0_34

; __device__ __forceinline__ float sigm(float v) { return __builtin_amdgcn_rcpf(1.0f + __builtin_amdgcn_exp2f(-LOG2E * v)); }
; __device__ __forceinline__ unsigned cvt_pk_bf16(float lo, float hi) { f32x2_t v = {lo, hi}; bf16x2_t b = __builtin_convertvector(v, bf16x2_t); return __builtin_bit_cast(unsigned, b); }
; #define EPI_FENCE() asm volatile("" ::: "memory")
; #define EPI_LANE() int t__ = threadIdx.x; asm volatile("" : "+v"(t__)); const int wid__ = __builtin_amdgcn_readfirstlane(t__ >> 6); wr = wid__ >> 2; wc = wid__ & 3; fr = t__ & 15; fq = (t__ & 63) >> 4
; template <int MODE> __device__ __forceinline__ float actf(float v) {
;     if (MODE == 1) return v * sigm(v);
;     if (MODE == 2) return fminf(1.0f + __builtin_amdgcn_exp2f(-LOG2E * v), 1e30f);
;     if (MODE == 3) return v * QSCALE;
;     return v;
; }
;     template <int MODE> __device__ __forceinline__ void run(const f32x4 (&acc)[2][2][4][2], const Unit& u, int wr, int wc, int fr, int fq) const {
;         EPI_LANE();
;         const int pn = u.pn, colt = pn * BM, t = colt >> 9;
;         char* base = (MODE == 2) ? (char*)(O + (size_t)6 * ((size_t)MTOK * 512)) + ((size_t)(((pn - 12) * 128 + u.pm) * 8 + wid__)) * 16384
;                                  : (char*)(O + (size_t)t * ((size_t)MTOK * 512) + (size_t)u.pm * BM * 512 + (colt & 511));
;         unsigned off0 = (MODE == 2) ? (unsigned)((t__ & 63) * 16) : (unsigned)((wr * 64 + fr) * 512 + wc * 32 + 8 * fq) * 2u; asm volatile("" : "+v"(off0));
; #pragma unroll
;         for (int bj = 0; bj < 2; ++bj) {
; #pragma unroll
;             for (int ai = 0; ai < 2; ++ai)
; #pragma unroll
;                 for (int m = 0; m < 4; ++m) { const unsigned off = off0 + ((MODE == 2) ? (unsigned)(((ai * 4 + m) * 2 + bj) * 1024) : (unsigned)((ai * HALF + m * 16) * 512 + bj * HALF) * 2u);
;                     const f32x4 v0 = acc[ai][bj][m][0], v1 = acc[ai][bj][m][1];
;                     u32x4 w; w.x = cvt_pk_bf16(actf<MODE>(v0[0]), actf<MODE>(v0[1])); w.y = cvt_pk_bf16(actf<MODE>(v0[2]), actf<MODE>(v0[3]));
;                     w.z = cvt_pk_bf16(actf<MODE>(v1[0]), actf<MODE>(v1[1])); w.w = cvt_pk_bf16(actf<MODE>(v1[2]), actf<MODE>(v1[3]));
;                     *(u32x4*)(base + off) = w; }
;             EPI_FENCE();
;         }
;     }
.LBB0_403:
	v_mul_f32_e32 v12, 0xbfb8aa3b, v12
	v_mul_f32_e32 v13, 0xbfb8aa3b, v13
	v_exp_f32_e32 v12, v12
	v_exp_f32_e32 v13, v13
	v_mul_f32_e32 v14, 0xbfb8aa3b, v14
	v_mul_f32_e32 v15, 0xbfb8aa3b, v15
	v_mul_f32_e32 v8, 0xbfb8aa3b, v8
	v_mul_f32_e32 v9, 0xbfb8aa3b, v9
	v_exp_f32_e32 v14, v14
	v_exp_f32_e32 v15, v15
	v_exp_f32_e32 v8, v8
	v_exp_f32_e32 v9, v9
	v_mul_f32_e32 v10, 0xbfb8aa3b, v10
	v_mul_f32_e32 v11, 0xbfb8aa3b, v11
	v_add_f32_e32 v12, 1.0, v12
	v_add_f32_e32 v13, 1.0, v13
	v_exp_f32_e32 v10, v10
	v_exp_f32_e32 v11, v11
	v_mul_f32_e32 v76, 0xbfb8aa3b, v76
	v_mul_f32_e32 v77, 0xbfb8aa3b, v77
	v_min_f32_e32 v12, 0x7149f2ca, v12
	v_min_f32_e32 v13, 0x7149f2ca, v13
	v_exp_f32_e32 v76, v76
	v_exp_f32_e32 v77, v77
	v_cvt_pk_bf16_f32 v12, v12, v13
	v_add_f32_e32 v13, 1.0, v14
	v_add_f32_e32 v14, 1.0, v15
	v_add_f32_e32 v8, 1.0, v8
	v_add_f32_e32 v9, 1.0, v9
	v_mul_f32_e32 v78, 0xbfb8aa3b, v78
	v_mul_f32_e32 v79, 0xbfb8aa3b, v79
	v_mul_f32_e32 v72, 0xbfb8aa3b, v72
	v_mul_f32_e32 v73, 0xbfb8aa3b, v73
	v_min_f32_e32 v13, 0x7149f2ca, v13
	v_min_f32_e32 v14, 0x7149f2ca, v14
	v_min_f32_e32 v8, 0x7149f2ca, v8
	v_min_f32_e32 v9, 0x7149f2ca, v9
	v_mov_b32_e32 v142, v212
	s_lshl_b32 s60, s72, 7
	v_exp_f32_e32 v78, v78
	v_exp_f32_e32 v79, v79
	v_exp_f32_e32 v72, v72
	v_exp_f32_e32 v73, v73
	v_cvt_pk_bf16_f32 v13, v13, v14
	v_cvt_pk_bf16_f32 v14, v8, v9
	v_add_f32_e32 v8, 1.0, v10
	v_add_f32_e32 v9, 1.0, v11
	s_add_i32 s60, s60, s54
	v_readfirstlane_b32 s55, v142
	v_mul_f32_e32 v74, 0xbfb8aa3b, v74
	v_mul_f32_e32 v75, 0xbfb8aa3b, v75
	v_min_f32_e32 v8, 0x7149f2ca, v8
	v_min_f32_e32 v9, 0x7149f2ca, v9
	s_ashr_i32 s55, s55, 6
	s_lshl_b32 s54, s60, 3
	v_add_f32_e32 v76, 1.0, v76
	v_add_f32_e32 v77, 1.0, v77
	v_exp_f32_e32 v74, v74
	v_exp_f32_e32 v75, v75
	v_cvt_pk_bf16_f32 v15, v8, v9
	v_mul_f32_e32 v8, 0xbfb8aa3b, v68
	v_mul_f32_e32 v9, 0xbfb8aa3b, v69
	s_nop 0
	v_min_f32_e32 v76, 0x7149f2ca, v76
	v_min_f32_e32 v77, 0x7149f2ca, v77
	v_exp_f32_e32 v8, v8
	v_exp_f32_e32 v9, v9
	s_addk_i32 s54, 0xd000
	v_cvt_pk_bf16_f32 v76, v76, v77
	v_add_f32_e32 v77, 1.0, v78
	v_add_f32_e32 v78, 1.0, v79
	v_add_f32_e32 v72, 1.0, v72
	v_add_f32_e32 v73, 1.0, v73
	v_mul_f32_e32 v10, 0xbfb8aa3b, v70
	v_mul_f32_e32 v11, 0xbfb8aa3b, v71
	s_ashr_i32 s55, s54, 31
	v_min_f32_e32 v77, 0x7149f2ca, v77
	v_min_f32_e32 v78, 0x7149f2ca, v78
	v_min_f32_e32 v72, 0x7149f2ca, v72
	v_min_f32_e32 v73, 0x7149f2ca, v73
	v_exp_f32_e32 v10, v10
	v_exp_f32_e32 v11, v11
	s_lshl_b64 s[54:55], s[54:55], 14
	v_lshlrev_b32_e32 v142, 4, v142
	v_cvt_pk_bf16_f32 v77, v77, v78
	v_cvt_pk_bf16_f32 v78, v72, v73
	v_add_f32_e32 v72, 1.0, v74
	v_add_f32_e32 v73, 1.0, v75
	s_add_u32 s54, s33, s54
	v_and_b32_e32 v142, 0x3f0, v142
	v_and_b32_e32 v190, 15, v212
	v_lshlrev_b32_e32 v190, 9, v190
	v_and_b32_e32 v191, 0x30, v212
	v_or_b32_e32 v190, v190, v191
	v_and_b32_e32 v191, 0xc0, v212
	v_lshl_or_b32 v190, v191, 1, v190
	v_and_b32_e32 v191, 0x100, v212
	v_lshl_or_b32 v142, v191, 7, v190
	v_min_f32_e32 v72, 0x7149f2ca, v72
	v_min_f32_e32 v73, 0x7149f2ca, v73
	v_add_f32_e32 v8, 1.0, v8
	v_add_f32_e32 v9, 1.0, v9
	s_addc_u32 s55, s37, s55
	v_cvt_pk_bf16_f32 v79, v72, v73
	v_add_u32_e32 v72, 0x16000, v142
	v_min_f32_e32 v8, 0x7149f2ca, v8
	v_min_f32_e32 v9, 0x7149f2ca, v9
	v_mul_f32_e32 v126, 0xbfb8aa3b, v126
	v_mul_f32_e32 v127, 0xbfb8aa3b, v127
	v_mul_f32_e32 v118, 0xbfb8aa3b, v118
	v_mul_f32_e32 v119, 0xbfb8aa3b, v119
	v_mul_f32_e32 v110, 0xbfb8aa3b, v110
	v_mul_f32_e32 v111, 0xbfb8aa3b, v111
	v_mul_f32_e32 v102, 0xbfb8aa3b, v102
	v_mul_f32_e32 v103, 0xbfb8aa3b, v103
	v_mul_f32_e32 v92, 0xbfb8aa3b, v92
	v_mul_f32_e32 v93, 0xbfb8aa3b, v93
	v_mul_f32_e32 v84, 0xbfb8aa3b, v84
	v_mul_f32_e32 v85, 0xbfb8aa3b, v85
	global_store_dwordx4 v72, v[12:15], s[54:55]
	v_cvt_pk_bf16_f32 v8, v8, v9
	v_add_f32_e32 v9, 1.0, v10
	v_add_f32_e32 v10, 1.0, v11
	v_mul_f32_e32 v11, 0xbfb8aa3b, v64
	v_mul_f32_e32 v13, 0xbfb8aa3b, v65
	v_exp_f32_e32 v126, v126
	v_exp_f32_e32 v127, v127
	v_exp_f32_e32 v118, v118
	v_exp_f32_e32 v119, v119
	v_exp_f32_e32 v110, v110
	v_exp_f32_e32 v111, v111
	v_exp_f32_e32 v102, v102
	v_exp_f32_e32 v103, v103
	v_exp_f32_e32 v92, v92
	v_exp_f32_e32 v93, v93
	v_exp_f32_e32 v84, v84
	v_exp_f32_e32 v85, v85
	v_exp_f32_e32 v11, v11
	v_exp_f32_e32 v13, v13
	v_mul_f32_e32 v128, 0xbfb8aa3b, v128
	v_mul_f32_e32 v129, 0xbfb8aa3b, v129
	v_mul_f32_e32 v122, 0xbfb8aa3b, v122
	v_mul_f32_e32 v123, 0xbfb8aa3b, v123
	v_mul_f32_e32 v120, 0xbfb8aa3b, v120
	v_mul_f32_e32 v121, 0xbfb8aa3b, v121
	v_mul_f32_e32 v114, 0xbfb8aa3b, v114
	v_mul_f32_e32 v115, 0xbfb8aa3b, v115
	v_mul_f32_e32 v112, 0xbfb8aa3b, v112
	v_mul_f32_e32 v113, 0xbfb8aa3b, v113
	v_mul_f32_e32 v106, 0xbfb8aa3b, v106
	v_mul_f32_e32 v107, 0xbfb8aa3b, v107
	v_mul_f32_e32 v104, 0xbfb8aa3b, v104
	v_mul_f32_e32 v105, 0xbfb8aa3b, v105
	v_mul_f32_e32 v98, 0xbfb8aa3b, v98
	v_mul_f32_e32 v99, 0xbfb8aa3b, v99
	v_mul_f32_e32 v94, 0xbfb8aa3b, v94
	v_mul_f32_e32 v95, 0xbfb8aa3b, v95
	v_mul_f32_e32 v88, 0xbfb8aa3b, v88
	v_mul_f32_e32 v89, 0xbfb8aa3b, v89
	v_mul_f32_e32 v86, 0xbfb8aa3b, v86
	v_mul_f32_e32 v87, 0xbfb8aa3b, v87
	v_mul_f32_e32 v80, 0xbfb8aa3b, v80
	v_mul_f32_e32 v81, 0xbfb8aa3b, v81
	v_exp_f32_e32 v128, v128
	v_exp_f32_e32 v129, v129
	v_exp_f32_e32 v122, v122
	v_exp_f32_e32 v123, v123
	v_exp_f32_e32 v120, v120
	v_exp_f32_e32 v121, v121
	v_exp_f32_e32 v114, v114
	v_exp_f32_e32 v115, v115
	v_exp_f32_e32 v112, v112
	v_exp_f32_e32 v113, v113
	v_exp_f32_e32 v106, v106
	v_exp_f32_e32 v107, v107
	v_exp_f32_e32 v104, v104
	v_exp_f32_e32 v105, v105
	v_exp_f32_e32 v98, v98
	v_exp_f32_e32 v99, v99
	v_exp_f32_e32 v94, v94
	v_exp_f32_e32 v95, v95
	v_exp_f32_e32 v88, v88
; __device__ __forceinline__ float sigm(float v) { return __builtin_amdgcn_rcpf(1.0f + __builtin_amdgcn_exp2f(-LOG2E * v)); }
; __device__ __forceinline__ unsigned cvt_pk_bf16(float lo, float hi) { f32x2_t v = {lo, hi}; bf16x2_t b = __builtin_convertvector(v, bf16x2_t); return __builtin_bit_cast(unsigned, b); }
; #define EPI_FENCE() asm volatile("" ::: "memory")
; #define EPI_LANE() int t__ = threadIdx.x; asm volatile("" : "+v"(t__)); const int wid__ = __builtin_amdgcn_readfirstlane(t__ >> 6); wr = wid__ >> 2; wc = wid__ & 3; fr = t__ & 15; fq = (t__ & 63) >> 4
; template <int MODE> __device__ __forceinline__ float actf(float v) {
;     if (MODE == 1) return v * sigm(v);
;     if (MODE == 2) return fminf(1.0f + __builtin_amdgcn_exp2f(-LOG2E * v), 1e30f);
;     if (MODE == 3) return v * QSCALE;
;     return v;
; }
;     template <int MODE> __device__ __forceinline__ void run(const f32x4 (&acc)[2][2][4][2], const Unit& u, int wr, int wc, int fr, int fq) const {
;         EPI_LANE();
;         const int pn = u.pn, colt = pn * BM, t = colt >> 9;
;         char* base = (MODE == 2) ? (char*)(O + (size_t)6 * ((size_t)MTOK * 512)) + ((size_t)(((pn - 12) * 128 + u.pm) * 8 + wid__)) * 16384
;                                  : (char*)(O + (size_t)t * ((size_t)MTOK * 512) + (size_t)u.pm * BM * 512 + (colt & 511));
;         unsigned off0 = (MODE == 2) ? (unsigned)((t__ & 63) * 16) : (unsigned)((wr * 64 + fr) * 512 + wc * 32 + 8 * fq) * 2u; asm volatile("" : "+v"(off0));
; #pragma unroll
;         for (int bj = 0; bj < 2; ++bj) {
; #pragma unroll
;             for (int ai = 0; ai < 2; ++ai)
; #pragma unroll
;                 for (int m = 0; m < 4; ++m) { const unsigned off = off0 + ((MODE == 2) ? (unsigned)(((ai * 4 + m) * 2 + bj) * 1024) : (unsigned)((ai * HALF + m * 16) * 512 + bj * HALF) * 2u);
;                     const f32x4 v0 = acc[ai][bj][m][0], v1 = acc[ai][bj][m][1];
;                     u32x4 w; w.x = cvt_pk_bf16(actf<MODE>(v0[0]), actf<MODE>(v0[1])); w.y = cvt_pk_bf16(actf<MODE>(v0[2]), actf<MODE>(v0[3]));
;                     w.z = cvt_pk_bf16(actf<MODE>(v1[0]), actf<MODE>(v1[1])); w.w = cvt_pk_bf16(actf<MODE>(v1[2]), actf<MODE>(v1[3]));
;                     *(u32x4*)(base + off) = w; }
;             EPI_FENCE();
;         }
;     }
	v_exp_f32_e32 v89, v89
	v_exp_f32_e32 v86, v86
	v_exp_f32_e32 v87, v87
	v_exp_f32_e32 v80, v80
	v_exp_f32_e32 v81, v81
	v_mul_f32_e32 v124, 0xbfb8aa3b, v124
	v_mul_f32_e32 v125, 0xbfb8aa3b, v125
	v_mul_f32_e32 v116, 0xbfb8aa3b, v116
	v_mul_f32_e32 v117, 0xbfb8aa3b, v117
	v_mul_f32_e32 v108, 0xbfb8aa3b, v108
	v_mul_f32_e32 v109, 0xbfb8aa3b, v109
	v_mul_f32_e32 v100, 0xbfb8aa3b, v100
	v_mul_f32_e32 v101, 0xbfb8aa3b, v101
	v_mul_f32_e32 v90, 0xbfb8aa3b, v90
	v_mul_f32_e32 v91, 0xbfb8aa3b, v91
	v_mul_f32_e32 v82, 0xbfb8aa3b, v82
	v_mul_f32_e32 v83, 0xbfb8aa3b, v83
	v_min_f32_e32 v9, 0x7149f2ca, v9
	v_min_f32_e32 v10, 0x7149f2ca, v10
	v_add_f32_e32 v126, 1.0, v126
	v_add_f32_e32 v127, 1.0, v127
	v_exp_f32_e32 v124, v124
	v_exp_f32_e32 v125, v125
	v_add_f32_e32 v118, 1.0, v118
	v_add_f32_e32 v119, 1.0, v119
	v_exp_f32_e32 v116, v116
	v_exp_f32_e32 v117, v117
	v_add_f32_e32 v110, 1.0, v110
	v_add_f32_e32 v111, 1.0, v111
	v_exp_f32_e32 v108, v108
	v_exp_f32_e32 v109, v109
	v_add_f32_e32 v102, 1.0, v102
	v_add_f32_e32 v103, 1.0, v103
	v_exp_f32_e32 v100, v100
	v_exp_f32_e32 v101, v101
	v_add_f32_e32 v92, 1.0, v92
	v_add_f32_e32 v93, 1.0, v93
	v_exp_f32_e32 v90, v90
	v_exp_f32_e32 v91, v91
	v_add_f32_e32 v84, 1.0, v84
	v_add_f32_e32 v85, 1.0, v85
	v_exp_f32_e32 v82, v82
	v_exp_f32_e32 v83, v83
	v_cvt_pk_bf16_f32 v9, v9, v10
	v_add_f32_e32 v10, 1.0, v11
	v_add_f32_e32 v11, 1.0, v13
	v_mul_f32_e32 v13, 0xbfb8aa3b, v66
	v_mul_f32_e32 v14, 0xbfb8aa3b, v67
	v_min_f32_e32 v126, 0x7149f2ca, v126
	v_min_f32_e32 v127, 0x7149f2ca, v127
	v_min_f32_e32 v118, 0x7149f2ca, v118
	v_min_f32_e32 v119, 0x7149f2ca, v119
	v_min_f32_e32 v110, 0x7149f2ca, v110
	v_min_f32_e32 v111, 0x7149f2ca, v111
	v_min_f32_e32 v102, 0x7149f2ca, v102
	v_min_f32_e32 v103, 0x7149f2ca, v103
	v_min_f32_e32 v92, 0x7149f2ca, v92
	v_min_f32_e32 v93, 0x7149f2ca, v93
	v_min_f32_e32 v84, 0x7149f2ca, v84
	v_min_f32_e32 v85, 0x7149f2ca, v85
	v_exp_f32_e32 v13, v13
	v_exp_f32_e32 v14, v14
	v_cvt_pk_bf16_f32 v126, v126, v127
	v_add_f32_e32 v127, 1.0, v128
	v_add_f32_e32 v128, 1.0, v129
	v_add_f32_e32 v122, 1.0, v122
	v_add_f32_e32 v123, 1.0, v123
	v_cvt_pk_bf16_f32 v118, v118, v119
	v_add_f32_e32 v119, 1.0, v120
	v_add_f32_e32 v120, 1.0, v121
	v_add_f32_e32 v114, 1.0, v114
	v_add_f32_e32 v115, 1.0, v115
	v_cvt_pk_bf16_f32 v110, v110, v111
	v_add_f32_e32 v111, 1.0, v112
	v_add_f32_e32 v112, 1.0, v113
	v_add_f32_e32 v106, 1.0, v106
	v_add_f32_e32 v107, 1.0, v107
	v_cvt_pk_bf16_f32 v102, v102, v103
	v_add_f32_e32 v103, 1.0, v104
	v_add_f32_e32 v104, 1.0, v105
	v_add_f32_e32 v98, 1.0, v98
	v_add_f32_e32 v99, 1.0, v99
	v_cvt_pk_bf16_f32 v92, v92, v93
	v_add_f32_e32 v93, 1.0, v94
	v_add_f32_e32 v94, 1.0, v95
	v_add_f32_e32 v88, 1.0, v88
	v_add_f32_e32 v89, 1.0, v89
	v_cvt_pk_bf16_f32 v84, v84, v85
	v_add_f32_e32 v85, 1.0, v86
	v_add_f32_e32 v86, 1.0, v87
	v_add_f32_e32 v80, 1.0, v80
	v_add_f32_e32 v81, 1.0, v81
	v_min_f32_e32 v127, 0x7149f2ca, v127
	v_min_f32_e32 v128, 0x7149f2ca, v128
	v_min_f32_e32 v122, 0x7149f2ca, v122
	v_min_f32_e32 v123, 0x7149f2ca, v123
	v_min_f32_e32 v119, 0x7149f2ca, v119
	v_min_f32_e32 v120, 0x7149f2ca, v120
	v_min_f32_e32 v114, 0x7149f2ca, v114
	v_min_f32_e32 v115, 0x7149f2ca, v115
	v_min_f32_e32 v111, 0x7149f2ca, v111
	v_min_f32_e32 v112, 0x7149f2ca, v112
	v_min_f32_e32 v106, 0x7149f2ca, v106
	v_min_f32_e32 v107, 0x7149f2ca, v107
	v_min_f32_e32 v103, 0x7149f2ca, v103
	v_min_f32_e32 v104, 0x7149f2ca, v104
	v_min_f32_e32 v98, 0x7149f2ca, v98
	v_min_f32_e32 v99, 0x7149f2ca, v99
	v_min_f32_e32 v93, 0x7149f2ca, v93
	v_min_f32_e32 v94, 0x7149f2ca, v94
	v_min_f32_e32 v88, 0x7149f2ca, v88
	v_min_f32_e32 v89, 0x7149f2ca, v89
	v_min_f32_e32 v85, 0x7149f2ca, v85
	v_min_f32_e32 v86, 0x7149f2ca, v86
	v_min_f32_e32 v80, 0x7149f2ca, v80
	v_min_f32_e32 v81, 0x7149f2ca, v81
	v_cvt_pk_bf16_f32 v127, v127, v128
	v_cvt_pk_bf16_f32 v128, v122, v123
	v_add_f32_e32 v122, 1.0, v124
	v_add_f32_e32 v123, 1.0, v125
	v_cvt_pk_bf16_f32 v119, v119, v120
	v_cvt_pk_bf16_f32 v120, v114, v115
	v_add_f32_e32 v114, 1.0, v116
	v_add_f32_e32 v115, 1.0, v117
	v_cvt_pk_bf16_f32 v111, v111, v112
	v_cvt_pk_bf16_f32 v112, v106, v107
	v_add_f32_e32 v106, 1.0, v108
	v_add_f32_e32 v107, 1.0, v109
	v_cvt_pk_bf16_f32 v103, v103, v104
	v_cvt_pk_bf16_f32 v104, v98, v99
	v_add_f32_e32 v98, 1.0, v100
	v_add_f32_e32 v99, 1.0, v101
	v_cvt_pk_bf16_f32 v93, v93, v94
	v_cvt_pk_bf16_f32 v94, v88, v89
	v_add_f32_e32 v88, 1.0, v90
	v_add_f32_e32 v89, 1.0, v91
	v_cvt_pk_bf16_f32 v85, v85, v86
	v_cvt_pk_bf16_f32 v86, v80, v81
	v_add_f32_e32 v80, 1.0, v82
	v_add_f32_e32 v81, 1.0, v83
	v_min_f32_e32 v10, 0x7149f2ca, v10
	v_min_f32_e32 v11, 0x7149f2ca, v11
	v_min_f32_e32 v122, 0x7149f2ca, v122
	v_min_f32_e32 v123, 0x7149f2ca, v123
	v_min_f32_e32 v114, 0x7149f2ca, v114
	v_min_f32_e32 v115, 0x7149f2ca, v115
	v_min_f32_e32 v106, 0x7149f2ca, v106
	v_min_f32_e32 v107, 0x7149f2ca, v107
	v_min_f32_e32 v98, 0x7149f2ca, v98
	v_min_f32_e32 v99, 0x7149f2ca, v99
	v_min_f32_e32 v88, 0x7149f2ca, v88
	v_min_f32_e32 v89, 0x7149f2ca, v89
	v_min_f32_e32 v80, 0x7149f2ca, v80
	v_min_f32_e32 v81, 0x7149f2ca, v81
	v_cvt_pk_bf16_f32 v10, v10, v11
	v_add_f32_e32 v11, 1.0, v13
	v_add_f32_e32 v13, 1.0, v14
	v_cvt_pk_bf16_f32 v129, v122, v123
	v_add_u32_e32 v122, 0x2000, v142
	v_cvt_pk_bf16_f32 v121, v114, v115
	v_add_u32_e32 v114, 0x4000, v142
	v_cvt_pk_bf16_f32 v113, v106, v107
	v_add_u32_e32 v106, 0x6000, v142
	v_cvt_pk_bf16_f32 v105, v98, v99
	v_add_u32_e32 v98, 0x10000, v142
	v_cvt_pk_bf16_f32 v95, v88, v89
	v_add_u32_e32 v88, 0x12000, v142
	v_cvt_pk_bf16_f32 v87, v80, v81
	v_add_u32_e32 v80, 0x14000, v142
	v_min_f32_e32 v11, 0x7149f2ca, v11
; __device__ __forceinline__ float sigm(float v) { return __builtin_amdgcn_rcpf(1.0f + __builtin_amdgcn_exp2f(-LOG2E * v)); }
; __device__ __forceinline__ unsigned cvt_pk_bf16(float lo, float hi) { f32x2_t v = {lo, hi}; bf16x2_t b = __builtin_convertvector(v, bf16x2_t); return __builtin_bit_cast(unsigned, b); }
; #define EPI_FENCE() asm volatile("" ::: "memory")
; #define EPI_LANE() int t__ = threadIdx.x; asm volatile("" : "+v"(t__)); const int wid__ = __builtin_amdgcn_readfirstlane(t__ >> 6); wr = wid__ >> 2; wc = wid__ & 3; fr = t__ & 15; fq = (t__ & 63) >> 4
; template <int MODE> __device__ __forceinline__ float actf(float v) {
;     if (MODE == 1) return v * sigm(v);
;     if (MODE == 2) return fminf(1.0f + __builtin_amdgcn_exp2f(-LOG2E * v), 1e30f);
;     if (MODE == 3) return v * QSCALE;
;     return v;
; }
;     template <int MODE> __device__ __forceinline__ void run(const f32x4 (&acc)[2][2][4][2], const Unit& u, int wr, int wc, int fr, int fq) const {
;         EPI_LANE();
;         const int pn = u.pn, colt = pn * BM, t = colt >> 9;
;         char* base = (MODE == 2) ? (char*)(O + (size_t)6 * ((size_t)MTOK * 512)) + ((size_t)(((pn - 12) * 128 + u.pm) * 8 + wid__)) * 16384
;                                  : (char*)(O + (size_t)t * ((size_t)MTOK * 512) + (size_t)u.pm * BM * 512 + (colt & 511));
;         unsigned off0 = (MODE == 2) ? (unsigned)((t__ & 63) * 16) : (unsigned)((wr * 64 + fr) * 512 + wc * 32 + 8 * fq) * 2u; asm volatile("" : "+v"(off0));
; #pragma unroll
;         for (int bj = 0; bj < 2; ++bj) {
; #pragma unroll
;             for (int ai = 0; ai < 2; ++ai)
; #pragma unroll
;                 for (int m = 0; m < 4; ++m) { const unsigned off = off0 + ((MODE == 2) ? (unsigned)(((ai * 4 + m) * 2 + bj) * 1024) : (unsigned)((ai * HALF + m * 16) * 512 + bj * HALF) * 2u);
;                     const f32x4 v0 = acc[ai][bj][m][0], v1 = acc[ai][bj][m][1];
;                     u32x4 w; w.x = cvt_pk_bf16(actf<MODE>(v0[0]), actf<MODE>(v0[1])); w.y = cvt_pk_bf16(actf<MODE>(v0[2]), actf<MODE>(v0[3]));
;                     w.z = cvt_pk_bf16(actf<MODE>(v1[0]), actf<MODE>(v1[1])); w.w = cvt_pk_bf16(actf<MODE>(v1[2]), actf<MODE>(v1[3]));
;                     *(u32x4*)(base + off) = w; }
;             EPI_FENCE();
;         }
;     }
	v_min_f32_e32 v13, 0x7149f2ca, v13
	global_store_dwordx4 v142, v[126:129], s[54:55]
	global_store_dwordx4 v122, v[118:121], s[54:55]
	global_store_dwordx4 v114, v[110:113], s[54:55]
	global_store_dwordx4 v106, v[102:105], s[54:55]
	global_store_dwordx4 v98, v[92:95], s[54:55]
	global_store_dwordx4 v88, v[84:87], s[54:55]
	global_store_dwordx4 v80, v[76:79], s[54:55]
	v_add_u32_e32 v12, 0x40, v142
	v_cvt_pk_bf16_f32 v11, v11, v13
	global_store_dwordx4 v12, v[8:11], s[54:55]
	v_mul_f32_e32 v13, 0xbfb8aa3b, v57
	v_exp_f32_e32 v13, v13
	v_mul_f32_e32 v8, 0xbfb8aa3b, v60
	v_mul_f32_e32 v9, 0xbfb8aa3b, v61
	v_exp_f32_e32 v8, v8
	v_exp_f32_e32 v9, v9
	v_mul_f32_e32 v10, 0xbfb8aa3b, v62
	v_mul_f32_e32 v11, 0xbfb8aa3b, v63
	v_exp_f32_e32 v10, v10
	v_exp_f32_e32 v11, v11
	v_add_f32_e32 v8, 1.0, v8
	v_add_f32_e32 v9, 1.0, v9
	v_min_f32_e32 v8, 0x7149f2ca, v8
	v_min_f32_e32 v9, 0x7149f2ca, v9
	v_cvt_pk_bf16_f32 v8, v8, v9
	v_add_f32_e32 v9, 1.0, v10
	v_add_f32_e32 v10, 1.0, v11
	v_mul_f32_e32 v11, 0xbfb8aa3b, v56
	v_exp_f32_e32 v11, v11
	v_min_f32_e32 v9, 0x7149f2ca, v9
	v_min_f32_e32 v10, 0x7149f2ca, v10
	v_cvt_pk_bf16_f32 v9, v9, v10
	v_add_f32_e32 v10, 1.0, v11
	v_add_f32_e32 v11, 1.0, v13
	v_mul_f32_e32 v13, 0xbfb8aa3b, v58
	v_mul_f32_e32 v14, 0xbfb8aa3b, v59
	v_exp_f32_e32 v13, v13
	v_exp_f32_e32 v14, v14
	v_min_f32_e32 v10, 0x7149f2ca, v10
	v_min_f32_e32 v11, 0x7149f2ca, v11
	v_cvt_pk_bf16_f32 v10, v10, v11
	v_add_f32_e32 v11, 1.0, v13
	v_add_f32_e32 v13, 1.0, v14
	v_min_f32_e32 v11, 0x7149f2ca, v11
	v_min_f32_e32 v13, 0x7149f2ca, v13
	v_add_u32_e32 v12, 0x2040, v142
	v_cvt_pk_bf16_f32 v11, v11, v13
	global_store_dwordx4 v12, v[8:11], s[54:55]
	v_mul_f32_e32 v13, 0xbfb8aa3b, v49
	v_exp_f32_e32 v13, v13
	v_mul_f32_e32 v8, 0xbfb8aa3b, v52
	v_mul_f32_e32 v9, 0xbfb8aa3b, v53
	v_exp_f32_e32 v8, v8
	v_exp_f32_e32 v9, v9
	v_mul_f32_e32 v10, 0xbfb8aa3b, v54
	v_mul_f32_e32 v11, 0xbfb8aa3b, v55
	v_exp_f32_e32 v10, v10
	v_exp_f32_e32 v11, v11
	v_add_f32_e32 v8, 1.0, v8
	v_add_f32_e32 v9, 1.0, v9
	v_min_f32_e32 v8, 0x7149f2ca, v8
	v_min_f32_e32 v9, 0x7149f2ca, v9
	v_cvt_pk_bf16_f32 v8, v8, v9
	v_add_f32_e32 v9, 1.0, v10
	v_add_f32_e32 v10, 1.0, v11
	v_mul_f32_e32 v11, 0xbfb8aa3b, v48
	v_exp_f32_e32 v11, v11
	v_min_f32_e32 v9, 0x7149f2ca, v9
	v_min_f32_e32 v10, 0x7149f2ca, v10
	v_cvt_pk_bf16_f32 v9, v9, v10
	v_add_f32_e32 v10, 1.0, v11
	v_add_f32_e32 v11, 1.0, v13
	v_mul_f32_e32 v13, 0xbfb8aa3b, v50
	v_mul_f32_e32 v14, 0xbfb8aa3b, v51
	v_exp_f32_e32 v13, v13
	v_exp_f32_e32 v14, v14
	v_min_f32_e32 v10, 0x7149f2ca, v10
	v_min_f32_e32 v11, 0x7149f2ca, v11
	v_cvt_pk_bf16_f32 v10, v10, v11
	v_add_f32_e32 v11, 1.0, v13
	v_add_f32_e32 v13, 1.0, v14
	v_min_f32_e32 v11, 0x7149f2ca, v11
	v_min_f32_e32 v13, 0x7149f2ca, v13
	v_add_u32_e32 v12, 0x4040, v142
	v_cvt_pk_bf16_f32 v11, v11, v13
	global_store_dwordx4 v12, v[8:11], s[54:55]
	v_mul_f32_e32 v13, 0xbfb8aa3b, v41
	v_exp_f32_e32 v13, v13
	v_mul_f32_e32 v8, 0xbfb8aa3b, v44
	v_mul_f32_e32 v9, 0xbfb8aa3b, v45
	v_exp_f32_e32 v8, v8
	v_exp_f32_e32 v9, v9
	v_mul_f32_e32 v10, 0xbfb8aa3b, v46
	v_mul_f32_e32 v11, 0xbfb8aa3b, v47
	v_exp_f32_e32 v10, v10
	v_exp_f32_e32 v11, v11
	v_add_f32_e32 v8, 1.0, v8
	v_add_f32_e32 v9, 1.0, v9
	v_min_f32_e32 v8, 0x7149f2ca, v8
	v_min_f32_e32 v9, 0x7149f2ca, v9
	v_cvt_pk_bf16_f32 v8, v8, v9
	v_add_f32_e32 v9, 1.0, v10
	v_add_f32_e32 v10, 1.0, v11
	v_mul_f32_e32 v11, 0xbfb8aa3b, v40
	v_exp_f32_e32 v11, v11
	v_min_f32_e32 v9, 0x7149f2ca, v9
	v_min_f32_e32 v10, 0x7149f2ca, v10
	v_cvt_pk_bf16_f32 v9, v9, v10
	v_add_f32_e32 v10, 1.0, v11
	v_add_f32_e32 v11, 1.0, v13
	v_mul_f32_e32 v13, 0xbfb8aa3b, v42
	v_mul_f32_e32 v14, 0xbfb8aa3b, v43
	v_exp_f32_e32 v13, v13
	v_exp_f32_e32 v14, v14
	v_min_f32_e32 v10, 0x7149f2ca, v10
	v_min_f32_e32 v11, 0x7149f2ca, v11
	v_cvt_pk_bf16_f32 v10, v10, v11
	v_add_f32_e32 v11, 1.0, v13
	v_add_f32_e32 v13, 1.0, v14
	v_min_f32_e32 v11, 0x7149f2ca, v11
	v_min_f32_e32 v13, 0x7149f2ca, v13
	v_add_u32_e32 v12, 0x6040, v142
	v_cvt_pk_bf16_f32 v11, v11, v13
	global_store_dwordx4 v12, v[8:11], s[54:55]
	v_mul_f32_e32 v13, 0xbfb8aa3b, v33
	v_exp_f32_e32 v13, v13
	v_mul_f32_e32 v8, 0xbfb8aa3b, v36
	v_mul_f32_e32 v9, 0xbfb8aa3b, v37
	v_exp_f32_e32 v8, v8
	v_exp_f32_e32 v9, v9
	v_mul_f32_e32 v10, 0xbfb8aa3b, v38
	v_mul_f32_e32 v11, 0xbfb8aa3b, v39
	v_exp_f32_e32 v10, v10
	v_exp_f32_e32 v11, v11
	v_add_f32_e32 v8, 1.0, v8
; __device__ __forceinline__ float sigm(float v) { return __builtin_amdgcn_rcpf(1.0f + __builtin_amdgcn_exp2f(-LOG2E * v)); }
; __device__ __forceinline__ unsigned cvt_pk_bf16(float lo, float hi) { f32x2_t v = {lo, hi}; bf16x2_t b = __builtin_convertvector(v, bf16x2_t); return __builtin_bit_cast(unsigned, b); }
; #define EPI_FENCE() asm volatile("" ::: "memory")
; #define EPI_LANE() int t__ = threadIdx.x; asm volatile("" : "+v"(t__)); const int wid__ = __builtin_amdgcn_readfirstlane(t__ >> 6); wr = wid__ >> 2; wc = wid__ & 3; fr = t__ & 15; fq = (t__ & 63) >> 4
; template <int MODE> __device__ __forceinline__ float actf(float v) {
;     if (MODE == 1) return v * sigm(v);
;     if (MODE == 2) return fminf(1.0f + __builtin_amdgcn_exp2f(-LOG2E * v), 1e30f);
;     if (MODE == 3) return v * QSCALE;
;     return v;
; }
;     template <int MODE> __device__ __forceinline__ void run(const f32x4 (&acc)[2][2][4][2], const Unit& u, int wr, int wc, int fr, int fq) const {
;         EPI_LANE();
;         const int pn = u.pn, colt = pn * BM, t = colt >> 9;
;         char* base = (MODE == 2) ? (char*)(O + (size_t)6 * ((size_t)MTOK * 512)) + ((size_t)(((pn - 12) * 128 + u.pm) * 8 + wid__)) * 16384
;                                  : (char*)(O + (size_t)t * ((size_t)MTOK * 512) + (size_t)u.pm * BM * 512 + (colt & 511));
;         unsigned off0 = (MODE == 2) ? (unsigned)((t__ & 63) * 16) : (unsigned)((wr * 64 + fr) * 512 + wc * 32 + 8 * fq) * 2u; asm volatile("" : "+v"(off0));
; #pragma unroll
;         for (int bj = 0; bj < 2; ++bj) {
; #pragma unroll
;             for (int ai = 0; ai < 2; ++ai)
; #pragma unroll
;                 for (int m = 0; m < 4; ++m) { const unsigned off = off0 + ((MODE == 2) ? (unsigned)(((ai * 4 + m) * 2 + bj) * 1024) : (unsigned)((ai * HALF + m * 16) * 512 + bj * HALF) * 2u);
;                     const f32x4 v0 = acc[ai][bj][m][0], v1 = acc[ai][bj][m][1];
;                     u32x4 w; w.x = cvt_pk_bf16(actf<MODE>(v0[0]), actf<MODE>(v0[1])); w.y = cvt_pk_bf16(actf<MODE>(v0[2]), actf<MODE>(v0[3]));
;                     w.z = cvt_pk_bf16(actf<MODE>(v1[0]), actf<MODE>(v1[1])); w.w = cvt_pk_bf16(actf<MODE>(v1[2]), actf<MODE>(v1[3]));
;                     *(u32x4*)(base + off) = w; }
;             EPI_FENCE();
;         }
;     }
	v_add_f32_e32 v9, 1.0, v9
	v_min_f32_e32 v8, 0x7149f2ca, v8
	v_min_f32_e32 v9, 0x7149f2ca, v9
	v_cvt_pk_bf16_f32 v8, v8, v9
	v_add_f32_e32 v9, 1.0, v10
	v_add_f32_e32 v10, 1.0, v11
	v_mul_f32_e32 v11, 0xbfb8aa3b, v32
	v_exp_f32_e32 v11, v11
	v_min_f32_e32 v9, 0x7149f2ca, v9
	v_min_f32_e32 v10, 0x7149f2ca, v10
	v_cvt_pk_bf16_f32 v9, v9, v10
	v_add_f32_e32 v10, 1.0, v11
	v_add_f32_e32 v11, 1.0, v13
	v_mul_f32_e32 v13, 0xbfb8aa3b, v34
	v_mul_f32_e32 v14, 0xbfb8aa3b, v35
	v_exp_f32_e32 v13, v13
	v_exp_f32_e32 v14, v14
	v_min_f32_e32 v10, 0x7149f2ca, v10
	v_min_f32_e32 v11, 0x7149f2ca, v11
	v_cvt_pk_bf16_f32 v10, v10, v11
	v_add_f32_e32 v11, 1.0, v13
	v_add_f32_e32 v13, 1.0, v14
	v_min_f32_e32 v11, 0x7149f2ca, v11
	v_min_f32_e32 v13, 0x7149f2ca, v13
	v_add_u32_e32 v12, 0x10040, v142
	v_cvt_pk_bf16_f32 v11, v11, v13
	global_store_dwordx4 v12, v[8:11], s[54:55]
	v_mul_f32_e32 v13, 0xbfb8aa3b, v25
	v_exp_f32_e32 v13, v13
	v_mul_f32_e32 v8, 0xbfb8aa3b, v28
	v_mul_f32_e32 v9, 0xbfb8aa3b, v29
	v_exp_f32_e32 v8, v8
	v_exp_f32_e32 v9, v9
	v_mul_f32_e32 v10, 0xbfb8aa3b, v30
	v_mul_f32_e32 v11, 0xbfb8aa3b, v31
	v_exp_f32_e32 v10, v10
	v_exp_f32_e32 v11, v11
	v_add_f32_e32 v8, 1.0, v8
	v_add_f32_e32 v9, 1.0, v9
	v_min_f32_e32 v8, 0x7149f2ca, v8
	v_min_f32_e32 v9, 0x7149f2ca, v9
	v_cvt_pk_bf16_f32 v8, v8, v9
	v_add_f32_e32 v9, 1.0, v10
	v_add_f32_e32 v10, 1.0, v11
	v_mul_f32_e32 v11, 0xbfb8aa3b, v24
	v_exp_f32_e32 v11, v11
	v_min_f32_e32 v9, 0x7149f2ca, v9
	v_min_f32_e32 v10, 0x7149f2ca, v10
	v_cvt_pk_bf16_f32 v9, v9, v10
	v_add_f32_e32 v10, 1.0, v11
	v_add_f32_e32 v11, 1.0, v13
	v_mul_f32_e32 v13, 0xbfb8aa3b, v26
	v_mul_f32_e32 v14, 0xbfb8aa3b, v27
	v_exp_f32_e32 v13, v13
	v_exp_f32_e32 v14, v14
	v_min_f32_e32 v10, 0x7149f2ca, v10
	v_min_f32_e32 v11, 0x7149f2ca, v11
	v_cvt_pk_bf16_f32 v10, v10, v11
	v_add_f32_e32 v11, 1.0, v13
	v_add_f32_e32 v13, 1.0, v14
	v_min_f32_e32 v11, 0x7149f2ca, v11
	v_min_f32_e32 v13, 0x7149f2ca, v13
	v_add_u32_e32 v12, 0x12040, v142
	v_cvt_pk_bf16_f32 v11, v11, v13
	global_store_dwordx4 v12, v[8:11], s[54:55]
	v_mul_f32_e32 v13, 0xbfb8aa3b, v17
	v_exp_f32_e32 v13, v13
	v_mul_f32_e32 v8, 0xbfb8aa3b, v20
	v_mul_f32_e32 v9, 0xbfb8aa3b, v21
	v_exp_f32_e32 v8, v8
	v_exp_f32_e32 v9, v9
	v_mul_f32_e32 v10, 0xbfb8aa3b, v22
	v_mul_f32_e32 v11, 0xbfb8aa3b, v23
	v_exp_f32_e32 v10, v10
	v_exp_f32_e32 v11, v11
	v_add_f32_e32 v8, 1.0, v8
	v_add_f32_e32 v9, 1.0, v9
	v_min_f32_e32 v8, 0x7149f2ca, v8
	v_min_f32_e32 v9, 0x7149f2ca, v9
	v_cvt_pk_bf16_f32 v8, v8, v9
	v_add_f32_e32 v9, 1.0, v10
	v_add_f32_e32 v10, 1.0, v11
	v_mul_f32_e32 v11, 0xbfb8aa3b, v16
	v_exp_f32_e32 v11, v11
	v_mul_f32_e32 v4, 0xbfb8aa3b, v4
	v_mul_f32_e32 v5, 0xbfb8aa3b, v5
	v_exp_f32_e32 v4, v4
	v_exp_f32_e32 v5, v5
	v_min_f32_e32 v9, 0x7149f2ca, v9
	v_min_f32_e32 v10, 0x7149f2ca, v10
	v_mul_f32_e32 v6, 0xbfb8aa3b, v6
	v_mul_f32_e32 v7, 0xbfb8aa3b, v7
	v_mul_f32_e32 v0, 0xbfb8aa3b, v0
	v_mul_f32_e32 v1, 0xbfb8aa3b, v1
	v_cvt_pk_bf16_f32 v9, v9, v10
	v_add_f32_e32 v10, 1.0, v11
	v_add_f32_e32 v11, 1.0, v13
	v_mul_f32_e32 v13, 0xbfb8aa3b, v18
	v_mul_f32_e32 v14, 0xbfb8aa3b, v19
	v_exp_f32_e32 v6, v6
	v_exp_f32_e32 v7, v7
	v_exp_f32_e32 v0, v0
	v_exp_f32_e32 v1, v1
	v_exp_f32_e32 v13, v13
	v_exp_f32_e32 v14, v14
	v_mul_f32_e32 v2, 0xbfb8aa3b, v2
	v_mul_f32_e32 v3, 0xbfb8aa3b, v3
	v_add_f32_e32 v4, 1.0, v4
	v_add_f32_e32 v5, 1.0, v5
	v_exp_f32_e32 v2, v2
	v_exp_f32_e32 v3, v3
	v_min_f32_e32 v4, 0x7149f2ca, v4
	v_min_f32_e32 v5, 0x7149f2ca, v5
	v_min_f32_e32 v10, 0x7149f2ca, v10
	v_min_f32_e32 v11, 0x7149f2ca, v11
	v_cvt_pk_bf16_f32 v4, v4, v5
	v_add_f32_e32 v5, 1.0, v6
	v_add_f32_e32 v6, 1.0, v7
	v_add_f32_e32 v0, 1.0, v0
	v_add_f32_e32 v1, 1.0, v1
	v_cvt_pk_bf16_f32 v10, v10, v11
	v_add_f32_e32 v11, 1.0, v13
	v_add_f32_e32 v13, 1.0, v14
	v_min_f32_e32 v5, 0x7149f2ca, v5
	v_min_f32_e32 v6, 0x7149f2ca, v6
	v_min_f32_e32 v0, 0x7149f2ca, v0
	v_min_f32_e32 v1, 0x7149f2ca, v1
	v_min_f32_e32 v11, 0x7149f2ca, v11
	v_min_f32_e32 v13, 0x7149f2ca, v13
	v_cvt_pk_bf16_f32 v5, v5, v6
	v_cvt_pk_bf16_f32 v6, v0, v1
	v_add_f32_e32 v0, 1.0, v2
	v_add_f32_e32 v1, 1.0, v3
	v_add_u32_e32 v12, 0x14040, v142
	v_cvt_pk_bf16_f32 v11, v11, v13
	v_min_f32_e32 v0, 0x7149f2ca, v0
	v_min_f32_e32 v1, 0x7149f2ca, v1
	global_store_dwordx4 v12, v[8:11], s[54:55]
	v_cvt_pk_bf16_f32 v7, v0, v1
	s_nop 0
	v_add_u32_e32 v8, 0x16040, v142
	global_store_dwordx4 v8, v[4:7], s[54:55]
